# v31 = v30 + late six staging writes in load-completion order with a per-write counted vmcnt ladder
# baseline (speedup 1.0000x reference)
.LBB0_302:
	ds_read_b128 v[216:219], v176 offset:36864
	ds_read_b128 v[200:203], v188
	ds_read_b128 v[220:223], v176 offset:41472
	ds_read_b128 v[204:207], v188 offset:4608
	ds_read_b128 v[208:211], v188 offset:9216
	ds_read_b128 v[212:215], v187
	s_waitcnt lgkmcnt(4)
	v_mfma_f32_32x32x16_bf16 v[112:127], v[200:203], v[216:219], v[112:127]
	ds_read_b128 v[240:243], v176 offset:36896
	global_load_dwordx4 v[140:143], v190, s[42:43]
	s_waitcnt lgkmcnt(4)
	v_mfma_f32_32x32x16_bf16 v[96:111], v[200:203], v[220:223], v[96:111]
	ds_read_b128 v[224:227], v188 offset:32
	global_load_dwordx4 v[160:163], v191, s[42:43]
	s_waitcnt lgkmcnt(4)
	v_mfma_f32_32x32x16_bf16 v[80:95], v[204:207], v[216:219], v[80:95]
	ds_read_b128 v[244:247], v176 offset:41504
	global_load_dwordx4 v[168:171], v192, s[42:43]
	s_waitcnt lgkmcnt(5)
	v_mfma_f32_32x32x16_bf16 v[64:79], v[204:207], v[220:223], v[64:79]
	ds_read_b128 v[228:231], v188 offset:4640
	global_load_dwordx4 v[172:175], v193, s[42:43]
	s_waitcnt lgkmcnt(5)
	v_mfma_f32_32x32x16_bf16 v[48:63], v[208:211], v[216:219], v[48:63]
	ds_read_b128 v[232:235], v188 offset:9248
	global_load_dwordx4 v[152:155], v196, s[40:41]
	s_waitcnt lgkmcnt(6)
	v_mfma_f32_32x32x16_bf16 v[32:47], v[208:211], v[220:223], v[32:47]
	ds_read_b128 v[236:239], v187 offset:32
	global_load_dwordx4 v[156:159], v197, s[40:41]
	s_add_u32 s40, s40, 0x80
	s_addc_u32 s41, s41, 0
	s_add_u32 s42, s42, 0x80
	s_addc_u32 s43, s43, 0
	s_add_u32 s16, s16, 0x80
	s_waitcnt lgkmcnt(6)
	v_mfma_f32_32x32x16_bf16 v[16:31], v[212:215], v[216:219], v[16:31]
	s_waitcnt lgkmcnt(6)
	v_mfma_f32_32x32x16_bf16 v[0:15], v[212:215], v[220:223], v[0:15]
	s_waitcnt lgkmcnt(4)
	v_mfma_f32_32x32x16_bf16 v[112:127], v[224:227], v[240:243], v[112:127]
	ds_read_b128 v[200:203], v188 offset:64
	s_waitcnt lgkmcnt(4)
	v_mfma_f32_32x32x16_bf16 v[96:111], v[224:227], v[244:247], v[96:111]
	ds_read_b128 v[204:207], v188 offset:4672
	s_waitcnt lgkmcnt(4)
	v_mfma_f32_32x32x16_bf16 v[80:95], v[228:231], v[240:243], v[80:95]
	ds_read_b128 v[208:211], v188 offset:9280
	s_waitcnt lgkmcnt(5)
	v_mfma_f32_32x32x16_bf16 v[64:79], v[228:231], v[244:247], v[64:79]
	ds_read_b128 v[212:215], v187 offset:64
	s_waitcnt lgkmcnt(5)
	v_mfma_f32_32x32x16_bf16 v[48:63], v[232:235], v[240:243], v[48:63]
	ds_read_b128 v[216:219], v176 offset:36928
	s_waitcnt lgkmcnt(6)
	v_mfma_f32_32x32x16_bf16 v[32:47], v[232:235], v[244:247], v[32:47]
	ds_read_b128 v[220:223], v176 offset:41536
	s_waitcnt lgkmcnt(6)
	v_mfma_f32_32x32x16_bf16 v[16:31], v[236:239], v[240:243], v[16:31]
	s_waitcnt lgkmcnt(6)
	v_mfma_f32_32x32x16_bf16 v[0:15], v[236:239], v[244:247], v[0:15]
	s_waitcnt lgkmcnt(1)
	v_mfma_f32_32x32x16_bf16 v[112:127], v[200:203], v[216:219], v[112:127]
	ds_read_b128 v[224:227], v188 offset:96
	s_waitcnt lgkmcnt(1)
	v_mfma_f32_32x32x16_bf16 v[96:111], v[200:203], v[220:223], v[96:111]
	ds_read_b128 v[228:231], v188 offset:4704
	s_waitcnt lgkmcnt(3)
	v_mfma_f32_32x32x16_bf16 v[80:95], v[204:207], v[216:219], v[80:95]
	ds_read_b128 v[232:235], v188 offset:9312
	s_waitcnt lgkmcnt(3)
	v_mfma_f32_32x32x16_bf16 v[64:79], v[204:207], v[220:223], v[64:79]
	ds_read_b128 v[236:239], v187 offset:96
	s_waitcnt lgkmcnt(5)
	v_mfma_f32_32x32x16_bf16 v[48:63], v[208:211], v[216:219], v[48:63]
	ds_read_b128 v[240:243], v176 offset:36960
	s_waitcnt lgkmcnt(5)
	v_mfma_f32_32x32x16_bf16 v[32:47], v[208:211], v[220:223], v[32:47]
	ds_read_b128 v[244:247], v176 offset:41568
	s_waitcnt lgkmcnt(7)
	v_mfma_f32_32x32x16_bf16 v[16:31], v[212:215], v[216:219], v[16:31]
	s_waitcnt lgkmcnt(6)
	v_mfma_f32_32x32x16_bf16 v[0:15], v[212:215], v[220:223], v[0:15]
	s_waitcnt lgkmcnt(0)
	s_barrier
	s_waitcnt vmcnt(6)
	s_waitcnt lgkmcnt(1)
	v_mfma_f32_32x32x16_bf16 v[112:127], v[224:227], v[240:243], v[112:127]
	ds_write_b128 v189, v[164:167]
	ds_write_b128 v189, v[128:131] offset:4608
	s_waitcnt lgkmcnt(2)
	v_mfma_f32_32x32x16_bf16 v[96:111], v[224:227], v[244:247], v[96:111]
	ds_write_b128 v189, v[132:135] offset:9216
	global_load_dwordx4 v[164:167], v190, s[40:41]
	s_waitcnt lgkmcnt(4)
	v_mfma_f32_32x32x16_bf16 v[80:95], v[228:231], v[240:243], v[80:95]
	ds_write_b128 v189, v[136:139] offset:13824
	ds_write_b128 v189, v[144:147] offset:18432
	global_load_dwordx4 v[128:131], v191, s[40:41]
	s_waitcnt lgkmcnt(5)
	v_mfma_f32_32x32x16_bf16 v[64:79], v[228:231], v[244:247], v[64:79]
	ds_write_b128 v189, v[148:151] offset:23040
	global_load_dwordx4 v[132:135], v192, s[40:41]
	s_waitcnt lgkmcnt(7)
	v_mfma_f32_32x32x16_bf16 v[48:63], v[232:235], v[240:243], v[48:63]
	s_waitcnt vmcnt(8)
	ds_write_b128 v189, v[140:143] offset:36864
	s_waitcnt vmcnt(7)
	ds_write_b128 v189, v[160:163] offset:41472
	global_load_dwordx4 v[136:139], v193, s[40:41]
	s_waitcnt lgkmcnt(8)
	v_mfma_f32_32x32x16_bf16 v[32:47], v[232:235], v[244:247], v[32:47]
	s_waitcnt vmcnt(7)
	ds_write_b128 v189, v[168:171] offset:46080
	global_load_dwordx4 v[144:147], v194, s[40:41]
	s_waitcnt lgkmcnt(10)
	v_mfma_f32_32x32x16_bf16 v[16:31], v[236:239], v[240:243], v[16:31]
	s_waitcnt vmcnt(7)
	ds_write_b128 v189, v[172:175] offset:50688
	s_waitcnt vmcnt(6)
	ds_write_b128 v189, v[152:155] offset:27648
	global_load_dwordx4 v[148:151], v195, s[40:41]
	s_waitcnt lgkmcnt(11)
	v_mfma_f32_32x32x16_bf16 v[0:15], v[236:239], v[244:247], v[0:15]
	s_waitcnt vmcnt(6)
	ds_write_b128 v189, v[156:159] offset:32256
	s_waitcnt lgkmcnt(0)
	s_barrier
	s_cmpk_lg_i32 s16, 0x780
	s_cbranch_scc1 .LBB0_302
	ds_read_b128 v[216:219], v176 offset:36864
	ds_read_b128 v[200:203], v188
	ds_read_b128 v[220:223], v176 offset:41472
	ds_read_b128 v[204:207], v188 offset:4608
	ds_read_b128 v[208:211], v188 offset:9216
	ds_read_b128 v[212:215], v187
	s_waitcnt lgkmcnt(4)
	v_mfma_f32_32x32x16_bf16 v[112:127], v[200:203], v[216:219], v[112:127]
	ds_read_b128 v[240:243], v176 offset:36896
	s_waitcnt lgkmcnt(4)
	v_mfma_f32_32x32x16_bf16 v[96:111], v[200:203], v[220:223], v[96:111]
	ds_read_b128 v[224:227], v188 offset:32
	s_waitcnt lgkmcnt(4)
	v_mfma_f32_32x32x16_bf16 v[80:95], v[204:207], v[216:219], v[80:95]
	ds_read_b128 v[244:247], v176 offset:41504
	s_waitcnt lgkmcnt(5)
	v_mfma_f32_32x32x16_bf16 v[64:79], v[204:207], v[220:223], v[64:79]
	ds_read_b128 v[228:231], v188 offset:4640
	s_waitcnt lgkmcnt(5)
	v_mfma_f32_32x32x16_bf16 v[48:63], v[208:211], v[216:219], v[48:63]
	ds_read_b128 v[232:235], v188 offset:9248
	s_waitcnt lgkmcnt(6)
	v_mfma_f32_32x32x16_bf16 v[32:47], v[208:211], v[220:223], v[32:47]
	ds_read_b128 v[236:239], v187 offset:32
	s_waitcnt lgkmcnt(6)
	v_mfma_f32_32x32x16_bf16 v[16:31], v[212:215], v[216:219], v[16:31]
	s_waitcnt lgkmcnt(6)
	v_mfma_f32_32x32x16_bf16 v[0:15], v[212:215], v[220:223], v[0:15]
	s_waitcnt lgkmcnt(4)
	v_mfma_f32_32x32x16_bf16 v[112:127], v[224:227], v[240:243], v[112:127]
	ds_read_b128 v[200:203], v188 offset:64
	s_waitcnt lgkmcnt(4)
	v_mfma_f32_32x32x16_bf16 v[96:111], v[224:227], v[244:247], v[96:111]
	ds_read_b128 v[204:207], v188 offset:4672
	s_waitcnt lgkmcnt(4)
	v_mfma_f32_32x32x16_bf16 v[80:95], v[228:231], v[240:243], v[80:95]
	ds_read_b128 v[208:211], v188 offset:9280
	s_waitcnt lgkmcnt(5)
	v_mfma_f32_32x32x16_bf16 v[64:79], v[228:231], v[244:247], v[64:79]
	ds_read_b128 v[212:215], v187 offset:64
	s_waitcnt lgkmcnt(5)
	v_mfma_f32_32x32x16_bf16 v[48:63], v[232:235], v[240:243], v[48:63]
	ds_read_b128 v[216:219], v176 offset:36928
	s_waitcnt lgkmcnt(6)
	v_mfma_f32_32x32x16_bf16 v[32:47], v[232:235], v[244:247], v[32:47]
	ds_read_b128 v[220:223], v176 offset:41536
	s_waitcnt lgkmcnt(6)
	v_mfma_f32_32x32x16_bf16 v[16:31], v[236:239], v[240:243], v[16:31]
	s_waitcnt lgkmcnt(6)
	v_mfma_f32_32x32x16_bf16 v[0:15], v[236:239], v[244:247], v[0:15]
	s_waitcnt lgkmcnt(1)
	v_mfma_f32_32x32x16_bf16 v[112:127], v[200:203], v[216:219], v[112:127]
	ds_read_b128 v[224:227], v188 offset:96
	s_waitcnt lgkmcnt(1)
	v_mfma_f32_32x32x16_bf16 v[96:111], v[200:203], v[220:223], v[96:111]
	ds_read_b128 v[228:231], v188 offset:4704
	s_waitcnt lgkmcnt(3)
	v_mfma_f32_32x32x16_bf16 v[80:95], v[204:207], v[216:219], v[80:95]
	ds_read_b128 v[232:235], v188 offset:9312
	s_waitcnt lgkmcnt(3)
	v_mfma_f32_32x32x16_bf16 v[64:79], v[204:207], v[220:223], v[64:79]
	ds_read_b128 v[236:239], v187 offset:96
	s_waitcnt lgkmcnt(5)
	v_mfma_f32_32x32x16_bf16 v[48:63], v[208:211], v[216:219], v[48:63]
	ds_read_b128 v[240:243], v176 offset:36960
	s_waitcnt lgkmcnt(5)
	v_mfma_f32_32x32x16_bf16 v[32:47], v[208:211], v[220:223], v[32:47]
	ds_read_b128 v[244:247], v176 offset:41568
	s_waitcnt lgkmcnt(7)
	v_mfma_f32_32x32x16_bf16 v[16:31], v[212:215], v[216:219], v[16:31]
	s_waitcnt lgkmcnt(6)
	v_mfma_f32_32x32x16_bf16 v[0:15], v[212:215], v[220:223], v[0:15]
	s_waitcnt lgkmcnt(1)
	v_mfma_f32_32x32x16_bf16 v[112:127], v[224:227], v[240:243], v[112:127]
	s_waitcnt lgkmcnt(0)
	v_mfma_f32_32x32x16_bf16 v[96:111], v[224:227], v[244:247], v[96:111]
	s_waitcnt lgkmcnt(1)
	v_mfma_f32_32x32x16_bf16 v[80:95], v[228:231], v[240:243], v[80:95]
	s_waitcnt lgkmcnt(0)
	v_mfma_f32_32x32x16_bf16 v[64:79], v[228:231], v[244:247], v[64:79]
	s_waitcnt lgkmcnt(1)
	v_mfma_f32_32x32x16_bf16 v[48:63], v[232:235], v[240:243], v[48:63]
	s_waitcnt lgkmcnt(0)
	v_mfma_f32_32x32x16_bf16 v[32:47], v[232:235], v[244:247], v[32:47]
	s_waitcnt lgkmcnt(1)
	v_mfma_f32_32x32x16_bf16 v[16:31], v[236:239], v[240:243], v[16:31]
	s_waitcnt lgkmcnt(0)
	v_mfma_f32_32x32x16_bf16 v[0:15], v[236:239], v[244:247], v[0:15]
	s_waitcnt vmcnt(0)
	s_mul_i32 s44, s12, 0x1240
	s_add_u32 s40, s30, s44
	s_addc_u32 s41, s31, 0
	s_lshl_b32 s44, s8, 1
	s_add_u32 s40, s40, s44
	s_addc_u32 s41, s41, 0
	s_add_u32 s40, s40, 0x7157900
	s_addc_u32 s41, s41, 0
	v_and_b32_e32 v131, 15, v182
	v_lshrrev_b32_e32 v172, 4, v182
	v_lshl_add_u32 v130, v131, 3, s8
	s_movk_i32 s44, 0x920
	v_cmp_gt_u32_e64 s[42:43], s44, v130
	v_mul_u32_u24_e32 v164, 0x1240, v172
	v_lshl_add_u32 v164, v131, 4, v164
	v_add_u32_e32 v165, 0x12400, v164
	v_add_u32_e32 v166, 0x24800, v164
	v_add_u32_e32 v167, 0x36c00, v164
	v_add_u32_e32 v168, 0x92000, v164
	v_add_u32_e32 v169, 0xa4400, v164
	v_add_u32_e32 v170, 0xb6800, v164
	v_add_u32_e32 v171, 0xc8c00, v164
	v_mul_u32_u24_e32 v129, 0x110, v172
	v_lshl_add_u32 v129, v131, 4, v129
	v_lshrrev_b32_e32 v131, 7, v182
	v_bfe_u32 v172, v182, 5, 1
	v_lshlrev_b32_e32 v131, 6, v131
	v_lshl_or_b32 v131, v172, 2, v131
	v_mul_u32_u24_e32 v131, 136, v131
	v_and_b32_e32 v172, 0x5f, v182
	v_add_lshl_u32 v128, v131, v172, 1
	s_barrier
	v_cvt_pk_bf16_f32 v112, v112, v113
	v_cvt_pk_bf16_f32 v114, v114, v115
	v_cvt_pk_bf16_f32 v116, v116, v117
	v_cvt_pk_bf16_f32 v118, v118, v119
	v_cvt_pk_bf16_f32 v120, v120, v121
	v_cvt_pk_bf16_f32 v122, v122, v123
	v_cvt_pk_bf16_f32 v124, v124, v125
	v_cvt_pk_bf16_f32 v126, v126, v127
	v_cvt_pk_bf16_f32 v96, v96, v97
	v_cvt_pk_bf16_f32 v98, v98, v99
	v_cvt_pk_bf16_f32 v100, v100, v101
	v_cvt_pk_bf16_f32 v102, v102, v103
	v_cvt_pk_bf16_f32 v104, v104, v105
	v_cvt_pk_bf16_f32 v106, v106, v107
	v_cvt_pk_bf16_f32 v108, v108, v109
	v_cvt_pk_bf16_f32 v110, v110, v111
	v_cvt_pk_bf16_f32 v80, v80, v81
	v_cvt_pk_bf16_f32 v82, v82, v83
	v_cvt_pk_bf16_f32 v84, v84, v85
	v_cvt_pk_bf16_f32 v86, v86, v87
	v_cvt_pk_bf16_f32 v88, v88, v89
	v_cvt_pk_bf16_f32 v90, v90, v91
	v_cvt_pk_bf16_f32 v92, v92, v93
	v_cvt_pk_bf16_f32 v94, v94, v95
	v_cvt_pk_bf16_f32 v64, v64, v65
	v_cvt_pk_bf16_f32 v66, v66, v67
	v_cvt_pk_bf16_f32 v68, v68, v69
	v_cvt_pk_bf16_f32 v70, v70, v71
	v_cvt_pk_bf16_f32 v72, v72, v73
	v_cvt_pk_bf16_f32 v74, v74, v75
	v_cvt_pk_bf16_f32 v76, v76, v77
	v_cvt_pk_bf16_f32 v78, v78, v79
	ds_write_b16 v128, v112
	ds_write_b16_d16_hi v128, v112 offset:272
	ds_write_b16 v128, v114 offset:544
	ds_write_b16_d16_hi v128, v114 offset:816
	ds_write_b16 v128, v116 offset:2176
	ds_write_b16_d16_hi v128, v116 offset:2448
	ds_write_b16 v128, v118 offset:2720
	ds_write_b16_d16_hi v128, v118 offset:2992
	ds_write_b16 v128, v120 offset:4352
	ds_write_b16_d16_hi v128, v120 offset:4624
	ds_write_b16 v128, v122 offset:4896
	ds_write_b16_d16_hi v128, v122 offset:5168
	ds_write_b16 v128, v124 offset:6528
	ds_write_b16_d16_hi v128, v124 offset:6800
	ds_write_b16 v128, v126 offset:7072
	ds_write_b16_d16_hi v128, v126 offset:7344
	ds_write_b16 v128, v96 offset:64
	ds_write_b16_d16_hi v128, v96 offset:336
	ds_write_b16 v128, v98 offset:608
	ds_write_b16_d16_hi v128, v98 offset:880
	ds_write_b16 v128, v100 offset:2240
	ds_write_b16_d16_hi v128, v100 offset:2512
	ds_write_b16 v128, v102 offset:2784
	ds_write_b16_d16_hi v128, v102 offset:3056
	ds_write_b16 v128, v104 offset:4416
	ds_write_b16_d16_hi v128, v104 offset:4688
	ds_write_b16 v128, v106 offset:4960
	ds_write_b16_d16_hi v128, v106 offset:5232
	ds_write_b16 v128, v108 offset:6592
	ds_write_b16_d16_hi v128, v108 offset:6864
	ds_write_b16 v128, v110 offset:7136
	ds_write_b16_d16_hi v128, v110 offset:7408
	ds_write_b16 v128, v80 offset:8704
	ds_write_b16_d16_hi v128, v80 offset:8976
	ds_write_b16 v128, v82 offset:9248
	ds_write_b16_d16_hi v128, v82 offset:9520
	ds_write_b16 v128, v84 offset:10880
	ds_write_b16_d16_hi v128, v84 offset:11152
	ds_write_b16 v128, v86 offset:11424
	ds_write_b16_d16_hi v128, v86 offset:11696
	ds_write_b16 v128, v88 offset:13056
	ds_write_b16_d16_hi v128, v88 offset:13328
	ds_write_b16 v128, v90 offset:13600
	ds_write_b16_d16_hi v128, v90 offset:13872
	ds_write_b16 v128, v92 offset:15232
	ds_write_b16_d16_hi v128, v92 offset:15504
	ds_write_b16 v128, v94 offset:15776
	ds_write_b16_d16_hi v128, v94 offset:16048
	ds_write_b16 v128, v64 offset:8768
	ds_write_b16_d16_hi v128, v64 offset:9040
	ds_write_b16 v128, v66 offset:9312
	ds_write_b16_d16_hi v128, v66 offset:9584
	ds_write_b16 v128, v68 offset:10944
	ds_write_b16_d16_hi v128, v68 offset:11216
	ds_write_b16 v128, v70 offset:11488
	ds_write_b16_d16_hi v128, v70 offset:11760
	ds_write_b16 v128, v72 offset:13120
	ds_write_b16_d16_hi v128, v72 offset:13392
	ds_write_b16 v128, v74 offset:13664
	ds_write_b16_d16_hi v128, v74 offset:13936
	ds_write_b16 v128, v76 offset:15296
	ds_write_b16_d16_hi v128, v76 offset:15568
	ds_write_b16 v128, v78 offset:15840
	ds_write_b16_d16_hi v128, v78 offset:16112
	s_waitcnt lgkmcnt(0)
	s_barrier
	ds_read_b128 v[132:135], v129
	ds_read_b128 v[136:139], v129 offset:4352
	ds_read_b128 v[140:143], v129 offset:8704
	ds_read_b128 v[144:147], v129 offset:13056
	ds_read_b128 v[148:151], v129 offset:17408
	ds_read_b128 v[152:155], v129 offset:21760
	ds_read_b128 v[156:159], v129 offset:26112
	ds_read_b128 v[160:163], v129 offset:30464
	v_cvt_pk_bf16_f32 v48, v48, v49
	v_cvt_pk_bf16_f32 v50, v50, v51
	v_cvt_pk_bf16_f32 v52, v52, v53
	v_cvt_pk_bf16_f32 v54, v54, v55
	v_cvt_pk_bf16_f32 v56, v56, v57
	v_cvt_pk_bf16_f32 v58, v58, v59
	v_cvt_pk_bf16_f32 v60, v60, v61
	v_cvt_pk_bf16_f32 v62, v62, v63
	v_cvt_pk_bf16_f32 v32, v32, v33
	v_cvt_pk_bf16_f32 v34, v34, v35
	v_cvt_pk_bf16_f32 v36, v36, v37
	v_cvt_pk_bf16_f32 v38, v38, v39
	v_cvt_pk_bf16_f32 v40, v40, v41
	v_cvt_pk_bf16_f32 v42, v42, v43
	v_cvt_pk_bf16_f32 v44, v44, v45
	v_cvt_pk_bf16_f32 v46, v46, v47
	v_cvt_pk_bf16_f32 v16, v16, v17
	v_cvt_pk_bf16_f32 v18, v18, v19
	v_cvt_pk_bf16_f32 v20, v20, v21
	v_cvt_pk_bf16_f32 v22, v22, v23
	v_cvt_pk_bf16_f32 v24, v24, v25
	v_cvt_pk_bf16_f32 v26, v26, v27
	v_cvt_pk_bf16_f32 v28, v28, v29
	v_cvt_pk_bf16_f32 v30, v30, v31
	v_cvt_pk_bf16_f32 v0, v0, v1
	v_cvt_pk_bf16_f32 v2, v2, v3
	v_cvt_pk_bf16_f32 v4, v4, v5
	v_cvt_pk_bf16_f32 v6, v6, v7
	v_cvt_pk_bf16_f32 v8, v8, v9
	v_cvt_pk_bf16_f32 v10, v10, v11
	v_cvt_pk_bf16_f32 v12, v12, v13
	v_cvt_pk_bf16_f32 v14, v14, v15
	s_and_saveexec_b64 s[46:47], s[42:43]
	s_waitcnt lgkmcnt(7)
	global_store_dwordx4 v164, v[132:135], s[40:41]
	s_waitcnt lgkmcnt(6)
	global_store_dwordx4 v165, v[136:139], s[40:41]
	s_waitcnt lgkmcnt(5)
	global_store_dwordx4 v166, v[140:143], s[40:41]
	s_waitcnt lgkmcnt(4)
	global_store_dwordx4 v167, v[144:147], s[40:41]
	s_waitcnt lgkmcnt(3)
	global_store_dwordx4 v168, v[148:151], s[40:41]
	s_waitcnt lgkmcnt(2)
	global_store_dwordx4 v169, v[152:155], s[40:41]
	s_waitcnt lgkmcnt(1)
	global_store_dwordx4 v170, v[156:159], s[40:41]
	s_waitcnt lgkmcnt(0)
	global_store_dwordx4 v171, v[160:163], s[40:41]
	s_or_b64 exec, exec, s[46:47]
	s_barrier
	ds_write_b16 v128, v48
	ds_write_b16_d16_hi v128, v48 offset:272
	ds_write_b16 v128, v50 offset:544
	ds_write_b16_d16_hi v128, v50 offset:816
	ds_write_b16 v128, v52 offset:2176
	ds_write_b16_d16_hi v128, v52 offset:2448
	ds_write_b16 v128, v54 offset:2720
	ds_write_b16_d16_hi v128, v54 offset:2992
	ds_write_b16 v128, v56 offset:4352
	ds_write_b16_d16_hi v128, v56 offset:4624
	ds_write_b16 v128, v58 offset:4896
	ds_write_b16_d16_hi v128, v58 offset:5168
	ds_write_b16 v128, v60 offset:6528
	ds_write_b16_d16_hi v128, v60 offset:6800
	ds_write_b16 v128, v62 offset:7072
	ds_write_b16_d16_hi v128, v62 offset:7344
	ds_write_b16 v128, v32 offset:64
	ds_write_b16_d16_hi v128, v32 offset:336
	ds_write_b16 v128, v34 offset:608
	ds_write_b16_d16_hi v128, v34 offset:880
	ds_write_b16 v128, v36 offset:2240
	ds_write_b16_d16_hi v128, v36 offset:2512
	ds_write_b16 v128, v38 offset:2784
	ds_write_b16_d16_hi v128, v38 offset:3056
	ds_write_b16 v128, v40 offset:4416
	ds_write_b16_d16_hi v128, v40 offset:4688
	ds_write_b16 v128, v42 offset:4960
	ds_write_b16_d16_hi v128, v42 offset:5232
	ds_write_b16 v128, v44 offset:6592
	ds_write_b16_d16_hi v128, v44 offset:6864
	ds_write_b16 v128, v46 offset:7136
	ds_write_b16_d16_hi v128, v46 offset:7408
	ds_write_b16 v128, v16 offset:8704
	ds_write_b16_d16_hi v128, v16 offset:8976
	ds_write_b16 v128, v18 offset:9248
	ds_write_b16_d16_hi v128, v18 offset:9520
	ds_write_b16 v128, v20 offset:10880
	ds_write_b16_d16_hi v128, v20 offset:11152
	ds_write_b16 v128, v22 offset:11424
	ds_write_b16_d16_hi v128, v22 offset:11696
	ds_write_b16 v128, v24 offset:13056
	ds_write_b16_d16_hi v128, v24 offset:13328
	ds_write_b16 v128, v26 offset:13600
	ds_write_b16_d16_hi v128, v26 offset:13872
	ds_write_b16 v128, v28 offset:15232
	ds_write_b16_d16_hi v128, v28 offset:15504
	ds_write_b16 v128, v30 offset:15776
	ds_write_b16_d16_hi v128, v30 offset:16048
	ds_write_b16 v128, v0 offset:8768
	ds_write_b16_d16_hi v128, v0 offset:9040
	ds_write_b16 v128, v2 offset:9312
	ds_write_b16_d16_hi v128, v2 offset:9584
	ds_write_b16 v128, v4 offset:10944
	ds_write_b16_d16_hi v128, v4 offset:11216
	ds_write_b16 v128, v6 offset:11488
	ds_write_b16_d16_hi v128, v6 offset:11760
	ds_write_b16 v128, v8 offset:13120
	ds_write_b16_d16_hi v128, v8 offset:13392
	ds_write_b16 v128, v10 offset:13664
	ds_write_b16_d16_hi v128, v10 offset:13936
	ds_write_b16 v128, v12 offset:15296
	ds_write_b16_d16_hi v128, v12 offset:15568
	ds_write_b16 v128, v14 offset:15840
	ds_write_b16_d16_hi v128, v14 offset:16112
	s_waitcnt lgkmcnt(0)
	s_barrier
	ds_read_b128 v[132:135], v129
	ds_read_b128 v[136:139], v129 offset:4352
	ds_read_b128 v[140:143], v129 offset:8704
	ds_read_b128 v[144:147], v129 offset:13056
	ds_read_b128 v[148:151], v129 offset:17408
	ds_read_b128 v[152:155], v129 offset:21760
	ds_read_b128 v[156:159], v129 offset:26112
	ds_read_b128 v[160:163], v129 offset:30464
	v_add_u32_e32 v164, 0x49000, v164
	v_add_u32_e32 v165, 0x49000, v165
	v_add_u32_e32 v166, 0x49000, v166
	v_add_u32_e32 v167, 0x49000, v167
	v_add_u32_e32 v168, 0x49000, v168
	v_add_u32_e32 v169, 0x49000, v169
	v_add_u32_e32 v170, 0x49000, v170
	v_add_u32_e32 v171, 0x49000, v171
	s_and_saveexec_b64 s[46:47], s[42:43]
	s_waitcnt lgkmcnt(7)
	global_store_dwordx4 v164, v[132:135], s[40:41]
	s_waitcnt lgkmcnt(6)
	global_store_dwordx4 v165, v[136:139], s[40:41]
	s_waitcnt lgkmcnt(5)
	global_store_dwordx4 v166, v[140:143], s[40:41]
	s_waitcnt lgkmcnt(4)
	global_store_dwordx4 v167, v[144:147], s[40:41]
	s_waitcnt lgkmcnt(3)
	global_store_dwordx4 v168, v[148:151], s[40:41]
	s_waitcnt lgkmcnt(2)
	global_store_dwordx4 v169, v[152:155], s[40:41]
	s_waitcnt lgkmcnt(1)
	global_store_dwordx4 v170, v[156:159], s[40:41]
	s_waitcnt lgkmcnt(0)
	global_store_dwordx4 v171, v[160:163], s[40:41]
	s_or_b64 exec, exec, s[46:47]
	s_branch .Lmt4_tail_0

.LBB0_997:
	ds_read_b128 v[216:219], v188 offset:36864
	ds_read_b128 v[200:203], v187
	ds_read_b128 v[220:223], v188 offset:41472
	ds_read_b128 v[204:207], v187 offset:4608
	ds_read_b128 v[208:211], v187 offset:9216
	ds_read_b128 v[212:215], v176
	s_waitcnt lgkmcnt(4)
	v_mfma_f32_32x32x16_bf16 v[112:127], v[200:203], v[216:219], v[112:127]
	ds_read_b128 v[240:243], v188 offset:36896
	global_load_dwordx4 v[152:155], v190, s[40:41]
	s_waitcnt lgkmcnt(4)
	v_mfma_f32_32x32x16_bf16 v[96:111], v[200:203], v[220:223], v[96:111]
	ds_read_b128 v[224:227], v187 offset:32
	global_load_dwordx4 v[164:167], v191, s[40:41]
	s_waitcnt lgkmcnt(4)
	v_mfma_f32_32x32x16_bf16 v[80:95], v[204:207], v[216:219], v[80:95]
	ds_read_b128 v[244:247], v188 offset:41504
	global_load_dwordx4 v[168:171], v192, s[40:41]
	s_waitcnt lgkmcnt(5)
	v_mfma_f32_32x32x16_bf16 v[64:79], v[204:207], v[220:223], v[64:79]
	ds_read_b128 v[228:231], v187 offset:4640
	global_load_dwordx4 v[172:175], v193, s[40:41]
	s_waitcnt lgkmcnt(5)
	v_mfma_f32_32x32x16_bf16 v[48:63], v[208:211], v[216:219], v[48:63]
	ds_read_b128 v[232:235], v187 offset:9248
	global_load_dwordx4 v[148:151], v196, s[38:39]
	s_waitcnt lgkmcnt(6)
	v_mfma_f32_32x32x16_bf16 v[32:47], v[208:211], v[220:223], v[32:47]
	ds_read_b128 v[236:239], v176 offset:32
	global_load_dwordx4 v[156:159], v197, s[38:39]
	s_add_u32 s38, s38, 0x80
	s_addc_u32 s39, s39, 0
	s_add_u32 s40, s40, 0x80
	s_addc_u32 s41, s41, 0
	s_add_u32 s12, s12, 0x80
	s_waitcnt lgkmcnt(6)
	v_mfma_f32_32x32x16_bf16 v[16:31], v[212:215], v[216:219], v[16:31]
	s_waitcnt lgkmcnt(6)
	v_mfma_f32_32x32x16_bf16 v[0:15], v[212:215], v[220:223], v[0:15]
	s_waitcnt lgkmcnt(4)
	v_mfma_f32_32x32x16_bf16 v[112:127], v[224:227], v[240:243], v[112:127]
	ds_read_b128 v[200:203], v187 offset:64
	s_waitcnt lgkmcnt(4)
	v_mfma_f32_32x32x16_bf16 v[96:111], v[224:227], v[244:247], v[96:111]
	ds_read_b128 v[204:207], v187 offset:4672
	s_waitcnt lgkmcnt(4)
	v_mfma_f32_32x32x16_bf16 v[80:95], v[228:231], v[240:243], v[80:95]
	ds_read_b128 v[208:211], v187 offset:9280
	s_waitcnt lgkmcnt(5)
	v_mfma_f32_32x32x16_bf16 v[64:79], v[228:231], v[244:247], v[64:79]
	ds_read_b128 v[212:215], v176 offset:64
	s_waitcnt lgkmcnt(5)
	v_mfma_f32_32x32x16_bf16 v[48:63], v[232:235], v[240:243], v[48:63]
	ds_read_b128 v[216:219], v188 offset:36928
	s_waitcnt lgkmcnt(6)
	v_mfma_f32_32x32x16_bf16 v[32:47], v[232:235], v[244:247], v[32:47]
	ds_read_b128 v[220:223], v188 offset:41536
	s_waitcnt lgkmcnt(6)
	v_mfma_f32_32x32x16_bf16 v[16:31], v[236:239], v[240:243], v[16:31]
	s_waitcnt lgkmcnt(6)
	v_mfma_f32_32x32x16_bf16 v[0:15], v[236:239], v[244:247], v[0:15]
	s_waitcnt lgkmcnt(1)
	v_mfma_f32_32x32x16_bf16 v[112:127], v[200:203], v[216:219], v[112:127]
	ds_read_b128 v[224:227], v187 offset:96
	s_waitcnt lgkmcnt(1)
	v_mfma_f32_32x32x16_bf16 v[96:111], v[200:203], v[220:223], v[96:111]
	ds_read_b128 v[228:231], v187 offset:4704
	s_waitcnt lgkmcnt(3)
	v_mfma_f32_32x32x16_bf16 v[80:95], v[204:207], v[216:219], v[80:95]
	ds_read_b128 v[232:235], v187 offset:9312
	s_waitcnt lgkmcnt(3)
	v_mfma_f32_32x32x16_bf16 v[64:79], v[204:207], v[220:223], v[64:79]
	ds_read_b128 v[236:239], v176 offset:96
	s_waitcnt lgkmcnt(5)
	v_mfma_f32_32x32x16_bf16 v[48:63], v[208:211], v[216:219], v[48:63]
	ds_read_b128 v[240:243], v188 offset:36960
	s_waitcnt lgkmcnt(5)
	v_mfma_f32_32x32x16_bf16 v[32:47], v[208:211], v[220:223], v[32:47]
	ds_read_b128 v[244:247], v188 offset:41568
	s_waitcnt lgkmcnt(7)
	v_mfma_f32_32x32x16_bf16 v[16:31], v[212:215], v[216:219], v[16:31]
	s_waitcnt lgkmcnt(6)
	v_mfma_f32_32x32x16_bf16 v[0:15], v[212:215], v[220:223], v[0:15]
	s_waitcnt lgkmcnt(0)
	s_barrier
	s_waitcnt vmcnt(6)
	s_waitcnt lgkmcnt(1)
	v_mfma_f32_32x32x16_bf16 v[112:127], v[224:227], v[240:243], v[112:127]
	ds_write_b128 v189, v[160:163]
	ds_write_b128 v189, v[128:131] offset:4608
	s_waitcnt lgkmcnt(2)
	v_mfma_f32_32x32x16_bf16 v[96:111], v[224:227], v[244:247], v[96:111]
	ds_write_b128 v189, v[132:135] offset:9216
	global_load_dwordx4 v[160:163], v190, s[38:39]
	s_waitcnt lgkmcnt(4)
	v_mfma_f32_32x32x16_bf16 v[80:95], v[228:231], v[240:243], v[80:95]
	ds_write_b128 v189, v[136:139] offset:13824
	ds_write_b128 v189, v[140:143] offset:18432
	global_load_dwordx4 v[128:131], v191, s[38:39]
	s_waitcnt lgkmcnt(5)
	v_mfma_f32_32x32x16_bf16 v[64:79], v[228:231], v[244:247], v[64:79]
	ds_write_b128 v189, v[144:147] offset:23040
	global_load_dwordx4 v[132:135], v192, s[38:39]
	s_waitcnt lgkmcnt(7)
	v_mfma_f32_32x32x16_bf16 v[48:63], v[232:235], v[240:243], v[48:63]
	s_waitcnt vmcnt(8)
	ds_write_b128 v189, v[152:155] offset:36864
	s_waitcnt vmcnt(7)
	ds_write_b128 v189, v[164:167] offset:41472
	global_load_dwordx4 v[136:139], v193, s[38:39]
	s_waitcnt lgkmcnt(8)
	v_mfma_f32_32x32x16_bf16 v[32:47], v[232:235], v[244:247], v[32:47]
	s_waitcnt vmcnt(7)
	ds_write_b128 v189, v[168:171] offset:46080
	global_load_dwordx4 v[140:143], v194, s[38:39]
	s_waitcnt lgkmcnt(10)
	v_mfma_f32_32x32x16_bf16 v[16:31], v[236:239], v[240:243], v[16:31]
	s_waitcnt vmcnt(7)
	ds_write_b128 v189, v[172:175] offset:50688
	s_waitcnt vmcnt(6)
	ds_write_b128 v189, v[148:151] offset:27648
	global_load_dwordx4 v[144:147], v195, s[38:39]
	s_waitcnt lgkmcnt(11)
	v_mfma_f32_32x32x16_bf16 v[0:15], v[236:239], v[244:247], v[0:15]
	s_waitcnt vmcnt(6)
	ds_write_b128 v189, v[156:159] offset:32256
	s_waitcnt lgkmcnt(0)
	s_barrier
	s_cmpk_lg_i32 s12, 0x780
	s_cbranch_scc1 .LBB0_997
	ds_read_b128 v[216:219], v188 offset:36864
	ds_read_b128 v[200:203], v187
	ds_read_b128 v[220:223], v188 offset:41472
	ds_read_b128 v[204:207], v187 offset:4608
	ds_read_b128 v[208:211], v187 offset:9216
	ds_read_b128 v[212:215], v176
	s_waitcnt lgkmcnt(4)
	v_mfma_f32_32x32x16_bf16 v[112:127], v[200:203], v[216:219], v[112:127]
	ds_read_b128 v[240:243], v188 offset:36896
	s_waitcnt lgkmcnt(4)
	v_mfma_f32_32x32x16_bf16 v[96:111], v[200:203], v[220:223], v[96:111]
	ds_read_b128 v[224:227], v187 offset:32
	s_waitcnt lgkmcnt(4)
	v_mfma_f32_32x32x16_bf16 v[80:95], v[204:207], v[216:219], v[80:95]
	ds_read_b128 v[244:247], v188 offset:41504
	s_waitcnt lgkmcnt(5)
	v_mfma_f32_32x32x16_bf16 v[64:79], v[204:207], v[220:223], v[64:79]
	ds_read_b128 v[228:231], v187 offset:4640
	s_waitcnt lgkmcnt(5)
	v_mfma_f32_32x32x16_bf16 v[48:63], v[208:211], v[216:219], v[48:63]
	ds_read_b128 v[232:235], v187 offset:9248
	s_waitcnt lgkmcnt(6)
	v_mfma_f32_32x32x16_bf16 v[32:47], v[208:211], v[220:223], v[32:47]
	ds_read_b128 v[236:239], v176 offset:32
	s_waitcnt lgkmcnt(6)
	v_mfma_f32_32x32x16_bf16 v[16:31], v[212:215], v[216:219], v[16:31]
	s_waitcnt lgkmcnt(6)
	v_mfma_f32_32x32x16_bf16 v[0:15], v[212:215], v[220:223], v[0:15]
	s_waitcnt lgkmcnt(4)
	v_mfma_f32_32x32x16_bf16 v[112:127], v[224:227], v[240:243], v[112:127]
	ds_read_b128 v[200:203], v187 offset:64
	s_waitcnt lgkmcnt(4)
	v_mfma_f32_32x32x16_bf16 v[96:111], v[224:227], v[244:247], v[96:111]
	ds_read_b128 v[204:207], v187 offset:4672
	s_waitcnt lgkmcnt(4)
	v_mfma_f32_32x32x16_bf16 v[80:95], v[228:231], v[240:243], v[80:95]
	ds_read_b128 v[208:211], v187 offset:9280
	s_waitcnt lgkmcnt(5)
	v_mfma_f32_32x32x16_bf16 v[64:79], v[228:231], v[244:247], v[64:79]
	ds_read_b128 v[212:215], v176 offset:64
	s_waitcnt lgkmcnt(5)
	v_mfma_f32_32x32x16_bf16 v[48:63], v[232:235], v[240:243], v[48:63]
	ds_read_b128 v[216:219], v188 offset:36928
	s_waitcnt lgkmcnt(6)
	v_mfma_f32_32x32x16_bf16 v[32:47], v[232:235], v[244:247], v[32:47]
	ds_read_b128 v[220:223], v188 offset:41536
	s_waitcnt lgkmcnt(6)
	v_mfma_f32_32x32x16_bf16 v[16:31], v[236:239], v[240:243], v[16:31]
	s_waitcnt lgkmcnt(6)
	v_mfma_f32_32x32x16_bf16 v[0:15], v[236:239], v[244:247], v[0:15]
	s_waitcnt lgkmcnt(1)
	v_mfma_f32_32x32x16_bf16 v[112:127], v[200:203], v[216:219], v[112:127]
	ds_read_b128 v[224:227], v187 offset:96
	s_waitcnt lgkmcnt(1)
	v_mfma_f32_32x32x16_bf16 v[96:111], v[200:203], v[220:223], v[96:111]
	ds_read_b128 v[228:231], v187 offset:4704
	s_waitcnt lgkmcnt(3)
	v_mfma_f32_32x32x16_bf16 v[80:95], v[204:207], v[216:219], v[80:95]
	ds_read_b128 v[232:235], v187 offset:9312
	s_waitcnt lgkmcnt(3)
	v_mfma_f32_32x32x16_bf16 v[64:79], v[204:207], v[220:223], v[64:79]
	ds_read_b128 v[236:239], v176 offset:96
	s_waitcnt lgkmcnt(5)
	v_mfma_f32_32x32x16_bf16 v[48:63], v[208:211], v[216:219], v[48:63]
	ds_read_b128 v[240:243], v188 offset:36960
	s_waitcnt lgkmcnt(5)
	v_mfma_f32_32x32x16_bf16 v[32:47], v[208:211], v[220:223], v[32:47]
	ds_read_b128 v[244:247], v188 offset:41568
	s_waitcnt lgkmcnt(7)
	v_mfma_f32_32x32x16_bf16 v[16:31], v[212:215], v[216:219], v[16:31]
	s_waitcnt lgkmcnt(6)
	v_mfma_f32_32x32x16_bf16 v[0:15], v[212:215], v[220:223], v[0:15]
	s_waitcnt lgkmcnt(1)
	v_mfma_f32_32x32x16_bf16 v[112:127], v[224:227], v[240:243], v[112:127]
	s_waitcnt lgkmcnt(0)
	v_mfma_f32_32x32x16_bf16 v[96:111], v[224:227], v[244:247], v[96:111]
	s_waitcnt lgkmcnt(1)
	v_mfma_f32_32x32x16_bf16 v[80:95], v[228:231], v[240:243], v[80:95]
	s_waitcnt lgkmcnt(0)
	v_mfma_f32_32x32x16_bf16 v[64:79], v[228:231], v[244:247], v[64:79]
	s_waitcnt lgkmcnt(1)
	v_mfma_f32_32x32x16_bf16 v[48:63], v[232:235], v[240:243], v[48:63]
	s_waitcnt lgkmcnt(0)
	v_mfma_f32_32x32x16_bf16 v[32:47], v[232:235], v[244:247], v[32:47]
	s_waitcnt lgkmcnt(1)
	v_mfma_f32_32x32x16_bf16 v[16:31], v[236:239], v[240:243], v[16:31]
	s_waitcnt lgkmcnt(0)
	v_mfma_f32_32x32x16_bf16 v[0:15], v[236:239], v[244:247], v[0:15]
	s_waitcnt vmcnt(0)
	s_mul_i32 s42, s6, 0x2000
	s_add_u32 s44, s30, s42
	s_addc_u32 s45, s31, 0
	s_lshl_b32 s42, s58, 1
	s_add_u32 s44, s44, s42
	s_addc_u32 s45, s45, 0
	s_add_u32 s44, s44, 0x7157900
	s_addc_u32 s45, s45, 0
	s_mov_b32 s43, 1
	v_max_f32_e32 v112, 0, v112
	v_max_f32_e32 v113, 0, v113
	v_mul_f32_e32 v112, v112, v112
	v_mul_f32_e32 v113, v113, v113
	v_cvt_pk_bf16_f32 v190, v112, v113
	v_max_f32_e32 v114, 0, v114
	v_max_f32_e32 v115, 0, v115
	v_mul_f32_e32 v114, v114, v114
	v_mul_f32_e32 v115, v115, v115
	v_cvt_pk_bf16_f32 v191, v114, v115
	v_max_f32_e32 v116, 0, v116
	v_max_f32_e32 v117, 0, v117
	v_mul_f32_e32 v116, v116, v116
	v_mul_f32_e32 v117, v117, v117
	v_cvt_pk_bf16_f32 v192, v116, v117
	v_max_f32_e32 v118, 0, v118
	v_max_f32_e32 v119, 0, v119
	v_mul_f32_e32 v118, v118, v118
	v_mul_f32_e32 v119, v119, v119
	v_cvt_pk_bf16_f32 v193, v118, v119
	v_max_f32_e32 v120, 0, v120
	v_max_f32_e32 v121, 0, v121
	v_mul_f32_e32 v120, v120, v120
	v_mul_f32_e32 v121, v121, v121
	v_cvt_pk_bf16_f32 v194, v120, v121
	v_max_f32_e32 v122, 0, v122
	v_max_f32_e32 v123, 0, v123
	v_mul_f32_e32 v122, v122, v122
	v_mul_f32_e32 v123, v123, v123
	v_cvt_pk_bf16_f32 v195, v122, v123
	v_max_f32_e32 v124, 0, v124
	v_max_f32_e32 v125, 0, v125
	v_mul_f32_e32 v124, v124, v124
	v_mul_f32_e32 v125, v125, v125
	v_cvt_pk_bf16_f32 v196, v124, v125
	v_max_f32_e32 v126, 0, v126
	v_max_f32_e32 v127, 0, v127
	v_mul_f32_e32 v126, v126, v126
	v_mul_f32_e32 v127, v127, v127
	v_cvt_pk_bf16_f32 v197, v126, v127
	v_max_f32_e32 v96, 0, v96
	v_max_f32_e32 v97, 0, v97
	v_mul_f32_e32 v96, v96, v96
	v_mul_f32_e32 v97, v97, v97
	v_cvt_pk_bf16_f32 v198, v96, v97
	v_max_f32_e32 v98, 0, v98
	v_max_f32_e32 v99, 0, v99
	v_mul_f32_e32 v98, v98, v98
	v_mul_f32_e32 v99, v99, v99
	v_cvt_pk_bf16_f32 v199, v98, v99
	v_max_f32_e32 v100, 0, v100
	v_max_f32_e32 v101, 0, v101
	v_mul_f32_e32 v100, v100, v100
	v_mul_f32_e32 v101, v101, v101
	v_cvt_pk_bf16_f32 v200, v100, v101
	v_max_f32_e32 v102, 0, v102
	v_max_f32_e32 v103, 0, v103
	v_mul_f32_e32 v102, v102, v102
	v_mul_f32_e32 v103, v103, v103
	v_cvt_pk_bf16_f32 v201, v102, v103
	v_max_f32_e32 v104, 0, v104
	v_max_f32_e32 v105, 0, v105
	v_mul_f32_e32 v104, v104, v104
	v_mul_f32_e32 v105, v105, v105
	v_cvt_pk_bf16_f32 v202, v104, v105
	v_max_f32_e32 v106, 0, v106
	v_max_f32_e32 v107, 0, v107
	v_mul_f32_e32 v106, v106, v106
	v_mul_f32_e32 v107, v107, v107
	v_cvt_pk_bf16_f32 v203, v106, v107
	v_max_f32_e32 v108, 0, v108
	v_max_f32_e32 v109, 0, v109
	v_mul_f32_e32 v108, v108, v108
	v_mul_f32_e32 v109, v109, v109
	v_cvt_pk_bf16_f32 v204, v108, v109
	v_max_f32_e32 v110, 0, v110
	v_max_f32_e32 v111, 0, v111
	v_mul_f32_e32 v110, v110, v110
	v_mul_f32_e32 v111, v111, v111
	v_cvt_pk_bf16_f32 v205, v110, v111
	v_max_f32_e32 v80, 0, v80
	v_max_f32_e32 v81, 0, v81
	v_mul_f32_e32 v80, v80, v80
	v_mul_f32_e32 v81, v81, v81
	v_cvt_pk_bf16_f32 v206, v80, v81
	v_max_f32_e32 v82, 0, v82
	v_max_f32_e32 v83, 0, v83
	v_mul_f32_e32 v82, v82, v82
	v_mul_f32_e32 v83, v83, v83
	v_cvt_pk_bf16_f32 v207, v82, v83
	v_max_f32_e32 v84, 0, v84
	v_max_f32_e32 v85, 0, v85
	v_mul_f32_e32 v84, v84, v84
	v_mul_f32_e32 v85, v85, v85
	v_cvt_pk_bf16_f32 v208, v84, v85
	v_max_f32_e32 v86, 0, v86
	v_max_f32_e32 v87, 0, v87
	v_mul_f32_e32 v86, v86, v86
	v_mul_f32_e32 v87, v87, v87
	v_cvt_pk_bf16_f32 v209, v86, v87
	v_max_f32_e32 v88, 0, v88
	v_max_f32_e32 v89, 0, v89
	v_mul_f32_e32 v88, v88, v88
	v_mul_f32_e32 v89, v89, v89
	v_cvt_pk_bf16_f32 v210, v88, v89
	v_max_f32_e32 v90, 0, v90
	v_max_f32_e32 v91, 0, v91
	v_mul_f32_e32 v90, v90, v90
	v_mul_f32_e32 v91, v91, v91
	v_cvt_pk_bf16_f32 v211, v90, v91
	v_max_f32_e32 v92, 0, v92
	v_max_f32_e32 v93, 0, v93
	v_mul_f32_e32 v92, v92, v92
	v_mul_f32_e32 v93, v93, v93
	v_cvt_pk_bf16_f32 v212, v92, v93
	v_max_f32_e32 v94, 0, v94
	v_max_f32_e32 v95, 0, v95
	v_mul_f32_e32 v94, v94, v94
	v_mul_f32_e32 v95, v95, v95
	v_cvt_pk_bf16_f32 v213, v94, v95
	v_max_f32_e32 v64, 0, v64
	v_max_f32_e32 v65, 0, v65
	v_mul_f32_e32 v64, v64, v64
	v_mul_f32_e32 v65, v65, v65
	v_cvt_pk_bf16_f32 v214, v64, v65
	v_max_f32_e32 v66, 0, v66
	v_max_f32_e32 v67, 0, v67
	v_mul_f32_e32 v66, v66, v66
	v_mul_f32_e32 v67, v67, v67
	v_cvt_pk_bf16_f32 v215, v66, v67
	v_max_f32_e32 v68, 0, v68
	v_max_f32_e32 v69, 0, v69
	v_mul_f32_e32 v68, v68, v68
	v_mul_f32_e32 v69, v69, v69
	v_cvt_pk_bf16_f32 v216, v68, v69
	v_max_f32_e32 v70, 0, v70
	v_max_f32_e32 v71, 0, v71
	v_mul_f32_e32 v70, v70, v70
	v_mul_f32_e32 v71, v71, v71
	v_cvt_pk_bf16_f32 v217, v70, v71
	v_max_f32_e32 v72, 0, v72
	v_max_f32_e32 v73, 0, v73
	v_mul_f32_e32 v72, v72, v72
	v_mul_f32_e32 v73, v73, v73
	v_cvt_pk_bf16_f32 v218, v72, v73
	v_max_f32_e32 v74, 0, v74
	v_max_f32_e32 v75, 0, v75
	v_mul_f32_e32 v74, v74, v74
	v_mul_f32_e32 v75, v75, v75
	v_cvt_pk_bf16_f32 v219, v74, v75
	v_max_f32_e32 v76, 0, v76
	v_max_f32_e32 v77, 0, v77
	v_mul_f32_e32 v76, v76, v76
	v_mul_f32_e32 v77, v77, v77
	v_cvt_pk_bf16_f32 v220, v76, v77
	v_max_f32_e32 v78, 0, v78
	v_max_f32_e32 v79, 0, v79
	v_mul_f32_e32 v78, v78, v78
	v_mul_f32_e32 v79, v79, v79
	v_cvt_pk_bf16_f32 v221, v78, v79
	v_max_f32_e32 v48, 0, v48
	v_max_f32_e32 v49, 0, v49
	v_mul_f32_e32 v48, v48, v48
	v_mul_f32_e32 v49, v49, v49
	v_cvt_pk_bf16_f32 v222, v48, v49
	v_max_f32_e32 v50, 0, v50
	v_max_f32_e32 v51, 0, v51
	v_mul_f32_e32 v50, v50, v50
	v_mul_f32_e32 v51, v51, v51
	v_cvt_pk_bf16_f32 v223, v50, v51
	v_max_f32_e32 v52, 0, v52
	v_max_f32_e32 v53, 0, v53
	v_mul_f32_e32 v52, v52, v52
	v_mul_f32_e32 v53, v53, v53
	v_cvt_pk_bf16_f32 v224, v52, v53
	v_max_f32_e32 v54, 0, v54
	v_max_f32_e32 v55, 0, v55
	v_mul_f32_e32 v54, v54, v54
	v_mul_f32_e32 v55, v55, v55
	v_cvt_pk_bf16_f32 v225, v54, v55
	v_max_f32_e32 v56, 0, v56
	v_max_f32_e32 v57, 0, v57
	v_mul_f32_e32 v56, v56, v56
	v_mul_f32_e32 v57, v57, v57
	v_cvt_pk_bf16_f32 v226, v56, v57
	v_max_f32_e32 v58, 0, v58
	v_max_f32_e32 v59, 0, v59
	v_mul_f32_e32 v58, v58, v58
	v_mul_f32_e32 v59, v59, v59
	v_cvt_pk_bf16_f32 v227, v58, v59
	v_max_f32_e32 v60, 0, v60
	v_max_f32_e32 v61, 0, v61
	v_mul_f32_e32 v60, v60, v60
	v_mul_f32_e32 v61, v61, v61
	v_cvt_pk_bf16_f32 v228, v60, v61
	v_max_f32_e32 v62, 0, v62
	v_max_f32_e32 v63, 0, v63
	v_mul_f32_e32 v62, v62, v62
	v_mul_f32_e32 v63, v63, v63
	v_cvt_pk_bf16_f32 v229, v62, v63
	v_max_f32_e32 v32, 0, v32
	v_max_f32_e32 v33, 0, v33
	v_mul_f32_e32 v32, v32, v32
	v_mul_f32_e32 v33, v33, v33
	v_cvt_pk_bf16_f32 v230, v32, v33
	v_max_f32_e32 v34, 0, v34
	v_max_f32_e32 v35, 0, v35
	v_mul_f32_e32 v34, v34, v34
	v_mul_f32_e32 v35, v35, v35
	v_cvt_pk_bf16_f32 v231, v34, v35
	v_max_f32_e32 v36, 0, v36
	v_max_f32_e32 v37, 0, v37
	v_mul_f32_e32 v36, v36, v36
	v_mul_f32_e32 v37, v37, v37
	v_cvt_pk_bf16_f32 v232, v36, v37
	v_max_f32_e32 v38, 0, v38
	v_max_f32_e32 v39, 0, v39
	v_mul_f32_e32 v38, v38, v38
	v_mul_f32_e32 v39, v39, v39
	v_cvt_pk_bf16_f32 v233, v38, v39
	v_max_f32_e32 v40, 0, v40
	v_max_f32_e32 v41, 0, v41
	v_mul_f32_e32 v40, v40, v40
	v_mul_f32_e32 v41, v41, v41
	v_cvt_pk_bf16_f32 v234, v40, v41
	v_max_f32_e32 v42, 0, v42
	v_max_f32_e32 v43, 0, v43
	v_mul_f32_e32 v42, v42, v42
	v_mul_f32_e32 v43, v43, v43
	v_cvt_pk_bf16_f32 v235, v42, v43
	v_max_f32_e32 v44, 0, v44
	v_max_f32_e32 v45, 0, v45
	v_mul_f32_e32 v44, v44, v44
	v_mul_f32_e32 v45, v45, v45
	v_cvt_pk_bf16_f32 v236, v44, v45
	v_max_f32_e32 v46, 0, v46
	v_max_f32_e32 v47, 0, v47
	v_mul_f32_e32 v46, v46, v46
	v_mul_f32_e32 v47, v47, v47
	v_cvt_pk_bf16_f32 v237, v46, v47
	v_max_f32_e32 v16, 0, v16
	v_max_f32_e32 v17, 0, v17
	v_mul_f32_e32 v16, v16, v16
	v_mul_f32_e32 v17, v17, v17
	v_cvt_pk_bf16_f32 v238, v16, v17
	v_max_f32_e32 v18, 0, v18
	v_max_f32_e32 v19, 0, v19
	v_mul_f32_e32 v18, v18, v18
	v_mul_f32_e32 v19, v19, v19
	v_cvt_pk_bf16_f32 v239, v18, v19
	v_max_f32_e32 v20, 0, v20
	v_max_f32_e32 v21, 0, v21
	v_mul_f32_e32 v20, v20, v20
	v_mul_f32_e32 v21, v21, v21
	v_cvt_pk_bf16_f32 v240, v20, v21
	v_max_f32_e32 v22, 0, v22
	v_max_f32_e32 v23, 0, v23
	v_mul_f32_e32 v22, v22, v22
	v_mul_f32_e32 v23, v23, v23
	v_cvt_pk_bf16_f32 v241, v22, v23
	v_max_f32_e32 v24, 0, v24
	v_max_f32_e32 v25, 0, v25
	v_mul_f32_e32 v24, v24, v24
	v_mul_f32_e32 v25, v25, v25
	v_cvt_pk_bf16_f32 v242, v24, v25
	v_max_f32_e32 v26, 0, v26
	v_max_f32_e32 v27, 0, v27
	v_mul_f32_e32 v26, v26, v26
	v_mul_f32_e32 v27, v27, v27
	v_cvt_pk_bf16_f32 v243, v26, v27
	v_max_f32_e32 v28, 0, v28
	v_max_f32_e32 v29, 0, v29
	v_mul_f32_e32 v28, v28, v28
	v_mul_f32_e32 v29, v29, v29
	v_cvt_pk_bf16_f32 v244, v28, v29
	v_max_f32_e32 v30, 0, v30
	v_max_f32_e32 v31, 0, v31
	v_mul_f32_e32 v30, v30, v30
	v_mul_f32_e32 v31, v31, v31
	v_cvt_pk_bf16_f32 v245, v30, v31
	v_max_f32_e32 v0, 0, v0
	v_max_f32_e32 v1, 0, v1
	v_mul_f32_e32 v0, v0, v0
	v_mul_f32_e32 v1, v1, v1
	v_cvt_pk_bf16_f32 v246, v0, v1
	v_max_f32_e32 v2, 0, v2
	v_max_f32_e32 v3, 0, v3
	v_mul_f32_e32 v2, v2, v2
	v_mul_f32_e32 v3, v3, v3
	v_cvt_pk_bf16_f32 v247, v2, v3
	v_max_f32_e32 v4, 0, v4
	v_max_f32_e32 v5, 0, v5
	v_mul_f32_e32 v4, v4, v4
	v_mul_f32_e32 v5, v5, v5
	v_cvt_pk_bf16_f32 v248, v4, v5
	v_max_f32_e32 v6, 0, v6
	v_max_f32_e32 v7, 0, v7
	v_mul_f32_e32 v6, v6, v6
	v_mul_f32_e32 v7, v7, v7
	v_cvt_pk_bf16_f32 v249, v6, v7
	v_max_f32_e32 v8, 0, v8
	v_max_f32_e32 v9, 0, v9
	v_mul_f32_e32 v8, v8, v8
	v_mul_f32_e32 v9, v9, v9
	v_cvt_pk_bf16_f32 v250, v8, v9
	v_max_f32_e32 v10, 0, v10
	v_max_f32_e32 v11, 0, v11
	v_mul_f32_e32 v10, v10, v10
	v_mul_f32_e32 v11, v11, v11
	v_cvt_pk_bf16_f32 v251, v10, v11
	v_max_f32_e32 v12, 0, v12
	v_max_f32_e32 v13, 0, v13
	v_mul_f32_e32 v12, v12, v12
	v_mul_f32_e32 v13, v13, v13
	v_cvt_pk_bf16_f32 v252, v12, v13
	v_max_f32_e32 v14, 0, v14
	v_max_f32_e32 v15, 0, v15
	v_mul_f32_e32 v14, v14, v14
	v_mul_f32_e32 v15, v15, v15
	v_cvt_pk_bf16_f32 v253, v14, v15
	s_add_i32 s57, s57, s22
	s_add_i32 s56, s56, s22
	s_cmpk_lt_u32 s57, 0x240
	s_cbranch_scc1 .LBB0_996
	v_and_b32_e32 v3, 15, v182
	v_lshrrev_b32_e32 v4, 4, v182
	v_mul_u32_u24_e32 v2, 0x2000, v4
	v_lshl_add_u32 v2, v3, 4, v2
	v_mul_u32_u24_e32 v1, 0x110, v4
	v_lshl_add_u32 v1, v3, 4, v1
	v_lshrrev_b32_e32 v3, 7, v182
	v_bfe_u32 v4, v182, 5, 1
	v_lshlrev_b32_e32 v3, 6, v3
	v_lshl_or_b32 v3, v4, 2, v3
	v_mul_u32_u24_e32 v3, 136, v3
	v_and_b32_e32 v4, 0x5f, v182
	v_add_lshl_u32 v0, v3, v4, 1
	s_barrier
	ds_write_b16 v0, v190
	ds_write_b16_d16_hi v0, v190 offset:272
	ds_write_b16 v0, v191 offset:544
	ds_write_b16_d16_hi v0, v191 offset:816
	ds_write_b16 v0, v192 offset:2176
	ds_write_b16_d16_hi v0, v192 offset:2448
	ds_write_b16 v0, v193 offset:2720
	ds_write_b16_d16_hi v0, v193 offset:2992
	ds_write_b16 v0, v194 offset:4352
	ds_write_b16_d16_hi v0, v194 offset:4624
	ds_write_b16 v0, v195 offset:4896
	ds_write_b16_d16_hi v0, v195 offset:5168
	ds_write_b16 v0, v196 offset:6528
	ds_write_b16_d16_hi v0, v196 offset:6800
	ds_write_b16 v0, v197 offset:7072
	ds_write_b16_d16_hi v0, v197 offset:7344
	ds_write_b16 v0, v198 offset:64
	ds_write_b16_d16_hi v0, v198 offset:336
	ds_write_b16 v0, v199 offset:608
	ds_write_b16_d16_hi v0, v199 offset:880
	ds_write_b16 v0, v200 offset:2240
	ds_write_b16_d16_hi v0, v200 offset:2512
	ds_write_b16 v0, v201 offset:2784
	ds_write_b16_d16_hi v0, v201 offset:3056
	ds_write_b16 v0, v202 offset:4416
	ds_write_b16_d16_hi v0, v202 offset:4688
	ds_write_b16 v0, v203 offset:4960
	ds_write_b16_d16_hi v0, v203 offset:5232
	ds_write_b16 v0, v204 offset:6592
	ds_write_b16_d16_hi v0, v204 offset:6864
	ds_write_b16 v0, v205 offset:7136
	ds_write_b16_d16_hi v0, v205 offset:7408
	ds_write_b16 v0, v206 offset:8704
	ds_write_b16_d16_hi v0, v206 offset:8976
	ds_write_b16 v0, v207 offset:9248
	ds_write_b16_d16_hi v0, v207 offset:9520
	ds_write_b16 v0, v208 offset:10880
	ds_write_b16_d16_hi v0, v208 offset:11152
	ds_write_b16 v0, v209 offset:11424
	ds_write_b16_d16_hi v0, v209 offset:11696
	ds_write_b16 v0, v210 offset:13056
	ds_write_b16_d16_hi v0, v210 offset:13328
	ds_write_b16 v0, v211 offset:13600
	ds_write_b16_d16_hi v0, v211 offset:13872
	ds_write_b16 v0, v212 offset:15232
	ds_write_b16_d16_hi v0, v212 offset:15504
	ds_write_b16 v0, v213 offset:15776
	ds_write_b16_d16_hi v0, v213 offset:16048
	ds_write_b16 v0, v214 offset:8768
	ds_write_b16_d16_hi v0, v214 offset:9040
	ds_write_b16 v0, v215 offset:9312
	ds_write_b16_d16_hi v0, v215 offset:9584
	ds_write_b16 v0, v216 offset:10944
	ds_write_b16_d16_hi v0, v216 offset:11216
	ds_write_b16 v0, v217 offset:11488
	ds_write_b16_d16_hi v0, v217 offset:11760
	ds_write_b16 v0, v218 offset:13120
	ds_write_b16_d16_hi v0, v218 offset:13392
	ds_write_b16 v0, v219 offset:13664
	ds_write_b16_d16_hi v0, v219 offset:13936
	ds_write_b16 v0, v220 offset:15296
	ds_write_b16_d16_hi v0, v220 offset:15568
	ds_write_b16 v0, v221 offset:15840
	ds_write_b16_d16_hi v0, v221 offset:16112
	s_waitcnt lgkmcnt(0)
	s_barrier
	ds_read_b128 v[8:11], v1
	ds_read_b128 v[12:15], v1 offset:4352
	ds_read_b128 v[16:19], v1 offset:8704
	ds_read_b128 v[20:23], v1 offset:13056
	ds_read_b128 v[24:27], v1 offset:17408
	ds_read_b128 v[28:31], v1 offset:21760
	ds_read_b128 v[32:35], v1 offset:26112
	ds_read_b128 v[36:39], v1 offset:30464
	s_add_u32 s38, s44, 0x0
	s_addc_u32 s39, s45, 0
	s_waitcnt lgkmcnt(7)
	global_store_dwordx4 v2, v[8:11], s[38:39]
	s_add_u32 s38, s44, 0x20000
	s_addc_u32 s39, s45, 0
	s_waitcnt lgkmcnt(6)
	global_store_dwordx4 v2, v[12:15], s[38:39]
	s_add_u32 s38, s44, 0x40000
	s_addc_u32 s39, s45, 0
	s_waitcnt lgkmcnt(5)
	global_store_dwordx4 v2, v[16:19], s[38:39]
	s_add_u32 s38, s44, 0x60000
	s_addc_u32 s39, s45, 0
	s_waitcnt lgkmcnt(4)
	global_store_dwordx4 v2, v[20:23], s[38:39]
	s_add_u32 s38, s44, 0x100000
	s_addc_u32 s39, s45, 0
	s_waitcnt lgkmcnt(3)
	global_store_dwordx4 v2, v[24:27], s[38:39]
	s_add_u32 s38, s44, 0x120000
	s_addc_u32 s39, s45, 0
	s_waitcnt lgkmcnt(2)
	global_store_dwordx4 v2, v[28:31], s[38:39]
	s_add_u32 s38, s44, 0x140000
	s_addc_u32 s39, s45, 0
	s_waitcnt lgkmcnt(1)
	global_store_dwordx4 v2, v[32:35], s[38:39]
	s_add_u32 s38, s44, 0x160000
	s_addc_u32 s39, s45, 0
	s_waitcnt lgkmcnt(0)
	global_store_dwordx4 v2, v[36:39], s[38:39]
	s_barrier
	ds_write_b16 v0, v222
	ds_write_b16_d16_hi v0, v222 offset:272
	ds_write_b16 v0, v223 offset:544
	ds_write_b16_d16_hi v0, v223 offset:816
	ds_write_b16 v0, v224 offset:2176
	ds_write_b16_d16_hi v0, v224 offset:2448
	ds_write_b16 v0, v225 offset:2720
	ds_write_b16_d16_hi v0, v225 offset:2992
	ds_write_b16 v0, v226 offset:4352
	ds_write_b16_d16_hi v0, v226 offset:4624
	ds_write_b16 v0, v227 offset:4896
	ds_write_b16_d16_hi v0, v227 offset:5168
	ds_write_b16 v0, v228 offset:6528
	ds_write_b16_d16_hi v0, v228 offset:6800
	ds_write_b16 v0, v229 offset:7072
	ds_write_b16_d16_hi v0, v229 offset:7344
	ds_write_b16 v0, v230 offset:64
	ds_write_b16_d16_hi v0, v230 offset:336
	ds_write_b16 v0, v231 offset:608
	ds_write_b16_d16_hi v0, v231 offset:880
	ds_write_b16 v0, v232 offset:2240
	ds_write_b16_d16_hi v0, v232 offset:2512
	ds_write_b16 v0, v233 offset:2784
	ds_write_b16_d16_hi v0, v233 offset:3056
	ds_write_b16 v0, v234 offset:4416
	ds_write_b16_d16_hi v0, v234 offset:4688
	ds_write_b16 v0, v235 offset:4960
	ds_write_b16_d16_hi v0, v235 offset:5232
	ds_write_b16 v0, v236 offset:6592
	ds_write_b16_d16_hi v0, v236 offset:6864
	ds_write_b16 v0, v237 offset:7136
	ds_write_b16_d16_hi v0, v237 offset:7408
	ds_write_b16 v0, v238 offset:8704
	ds_write_b16_d16_hi v0, v238 offset:8976
	ds_write_b16 v0, v239 offset:9248
	ds_write_b16_d16_hi v0, v239 offset:9520
	ds_write_b16 v0, v240 offset:10880
	ds_write_b16_d16_hi v0, v240 offset:11152
	ds_write_b16 v0, v241 offset:11424
	ds_write_b16_d16_hi v0, v241 offset:11696
	ds_write_b16 v0, v242 offset:13056
	ds_write_b16_d16_hi v0, v242 offset:13328
	ds_write_b16 v0, v243 offset:13600
	ds_write_b16_d16_hi v0, v243 offset:13872
	ds_write_b16 v0, v244 offset:15232
	ds_write_b16_d16_hi v0, v244 offset:15504
	ds_write_b16 v0, v245 offset:15776
	ds_write_b16_d16_hi v0, v245 offset:16048
	ds_write_b16 v0, v246 offset:8768
	ds_write_b16_d16_hi v0, v246 offset:9040
	ds_write_b16 v0, v247 offset:9312
	ds_write_b16_d16_hi v0, v247 offset:9584
	ds_write_b16 v0, v248 offset:10944
	ds_write_b16_d16_hi v0, v248 offset:11216
	ds_write_b16 v0, v249 offset:11488
	ds_write_b16_d16_hi v0, v249 offset:11760
	ds_write_b16 v0, v250 offset:13120
	ds_write_b16_d16_hi v0, v250 offset:13392
	ds_write_b16 v0, v251 offset:13664
	ds_write_b16_d16_hi v0, v251 offset:13936
	ds_write_b16 v0, v252 offset:15296
	ds_write_b16_d16_hi v0, v252 offset:15568
	ds_write_b16 v0, v253 offset:15840
	ds_write_b16_d16_hi v0, v253 offset:16112
	s_waitcnt lgkmcnt(0)
	s_barrier
	ds_read_b128 v[8:11], v1
	ds_read_b128 v[12:15], v1 offset:4352
	ds_read_b128 v[16:19], v1 offset:8704
	ds_read_b128 v[20:23], v1 offset:13056
	ds_read_b128 v[24:27], v1 offset:17408
	ds_read_b128 v[28:31], v1 offset:21760
	ds_read_b128 v[32:35], v1 offset:26112
	ds_read_b128 v[36:39], v1 offset:30464
	s_add_u32 s38, s44, 0x80000
	s_addc_u32 s39, s45, 0
	s_waitcnt lgkmcnt(7)
	global_store_dwordx4 v2, v[8:11], s[38:39]
	s_add_u32 s38, s44, 0xa0000
	s_addc_u32 s39, s45, 0
	s_waitcnt lgkmcnt(6)
	global_store_dwordx4 v2, v[12:15], s[38:39]
	s_add_u32 s38, s44, 0xc0000
	s_addc_u32 s39, s45, 0
	s_waitcnt lgkmcnt(5)
	global_store_dwordx4 v2, v[16:19], s[38:39]
	s_add_u32 s38, s44, 0xe0000
	s_addc_u32 s39, s45, 0
	s_waitcnt lgkmcnt(4)
	global_store_dwordx4 v2, v[20:23], s[38:39]
	s_add_u32 s38, s44, 0x180000
	s_addc_u32 s39, s45, 0
	s_waitcnt lgkmcnt(3)
	global_store_dwordx4 v2, v[24:27], s[38:39]
	s_add_u32 s38, s44, 0x1a0000
	s_addc_u32 s39, s45, 0
	s_waitcnt lgkmcnt(2)
	global_store_dwordx4 v2, v[28:31], s[38:39]
	s_add_u32 s38, s44, 0x1c0000
	s_addc_u32 s39, s45, 0
	s_waitcnt lgkmcnt(1)
	global_store_dwordx4 v2, v[32:35], s[38:39]
	s_add_u32 s38, s44, 0x1e0000
	s_addc_u32 s39, s45, 0
	s_waitcnt lgkmcnt(0)
	global_store_dwordx4 v2, v[36:39], s[38:39]
	s_mov_b32 s43, 0
	s_branch .LBB0_989

.LBB0_1284:
	ds_read_b128 v[216:219], v176 offset:36864
	ds_read_b128 v[200:203], v188
	ds_read_b128 v[220:223], v176 offset:41472
	ds_read_b128 v[204:207], v188 offset:4608
	ds_read_b128 v[208:211], v188 offset:9216
	ds_read_b128 v[212:215], v187
	s_waitcnt lgkmcnt(4)
	v_mfma_f32_32x32x16_bf16 v[112:127], v[200:203], v[216:219], v[112:127]
	ds_read_b128 v[240:243], v176 offset:36896
	global_load_dwordx4 v[140:143], v190, s[44:45]
	s_waitcnt lgkmcnt(4)
	v_mfma_f32_32x32x16_bf16 v[96:111], v[200:203], v[220:223], v[96:111]
	ds_read_b128 v[224:227], v188 offset:32
	global_load_dwordx4 v[160:163], v191, s[44:45]
	s_waitcnt lgkmcnt(4)
	v_mfma_f32_32x32x16_bf16 v[80:95], v[204:207], v[216:219], v[80:95]
	ds_read_b128 v[244:247], v176 offset:41504
	global_load_dwordx4 v[168:171], v192, s[44:45]
	s_waitcnt lgkmcnt(5)
	v_mfma_f32_32x32x16_bf16 v[64:79], v[204:207], v[220:223], v[64:79]
	ds_read_b128 v[228:231], v188 offset:4640
	global_load_dwordx4 v[172:175], v193, s[44:45]
	s_waitcnt lgkmcnt(5)
	v_mfma_f32_32x32x16_bf16 v[48:63], v[208:211], v[216:219], v[48:63]
	ds_read_b128 v[232:235], v188 offset:9248
	global_load_dwordx4 v[152:155], v196, s[42:43]
	s_waitcnt lgkmcnt(6)
	v_mfma_f32_32x32x16_bf16 v[32:47], v[208:211], v[220:223], v[32:47]
	ds_read_b128 v[236:239], v187 offset:32
	global_load_dwordx4 v[156:159], v197, s[42:43]
	s_add_u32 s42, s42, 0x80
	s_addc_u32 s43, s43, 0
	s_add_u32 s44, s44, 0x80
	s_addc_u32 s45, s45, 0
	s_add_u32 s16, s16, 0x80
	s_waitcnt lgkmcnt(6)
	v_mfma_f32_32x32x16_bf16 v[16:31], v[212:215], v[216:219], v[16:31]
	s_waitcnt lgkmcnt(6)
	v_mfma_f32_32x32x16_bf16 v[0:15], v[212:215], v[220:223], v[0:15]
	s_waitcnt lgkmcnt(4)
	v_mfma_f32_32x32x16_bf16 v[112:127], v[224:227], v[240:243], v[112:127]
	ds_read_b128 v[200:203], v188 offset:64
	s_waitcnt lgkmcnt(4)
	v_mfma_f32_32x32x16_bf16 v[96:111], v[224:227], v[244:247], v[96:111]
	ds_read_b128 v[204:207], v188 offset:4672
	s_waitcnt lgkmcnt(4)
	v_mfma_f32_32x32x16_bf16 v[80:95], v[228:231], v[240:243], v[80:95]
	ds_read_b128 v[208:211], v188 offset:9280
	s_waitcnt lgkmcnt(5)
	v_mfma_f32_32x32x16_bf16 v[64:79], v[228:231], v[244:247], v[64:79]
	ds_read_b128 v[212:215], v187 offset:64
	s_waitcnt lgkmcnt(5)
	v_mfma_f32_32x32x16_bf16 v[48:63], v[232:235], v[240:243], v[48:63]
	ds_read_b128 v[216:219], v176 offset:36928
	s_waitcnt lgkmcnt(6)
	v_mfma_f32_32x32x16_bf16 v[32:47], v[232:235], v[244:247], v[32:47]
	ds_read_b128 v[220:223], v176 offset:41536
	s_waitcnt lgkmcnt(6)
	v_mfma_f32_32x32x16_bf16 v[16:31], v[236:239], v[240:243], v[16:31]
	s_waitcnt lgkmcnt(6)
	v_mfma_f32_32x32x16_bf16 v[0:15], v[236:239], v[244:247], v[0:15]
	s_waitcnt lgkmcnt(1)
	v_mfma_f32_32x32x16_bf16 v[112:127], v[200:203], v[216:219], v[112:127]
	ds_read_b128 v[224:227], v188 offset:96
	s_waitcnt lgkmcnt(1)
	v_mfma_f32_32x32x16_bf16 v[96:111], v[200:203], v[220:223], v[96:111]
	ds_read_b128 v[228:231], v188 offset:4704
	s_waitcnt lgkmcnt(3)
	v_mfma_f32_32x32x16_bf16 v[80:95], v[204:207], v[216:219], v[80:95]
	ds_read_b128 v[232:235], v188 offset:9312
	s_waitcnt lgkmcnt(3)
	v_mfma_f32_32x32x16_bf16 v[64:79], v[204:207], v[220:223], v[64:79]
	ds_read_b128 v[236:239], v187 offset:96
	s_waitcnt lgkmcnt(5)
	v_mfma_f32_32x32x16_bf16 v[48:63], v[208:211], v[216:219], v[48:63]
	ds_read_b128 v[240:243], v176 offset:36960
	s_waitcnt lgkmcnt(5)
	v_mfma_f32_32x32x16_bf16 v[32:47], v[208:211], v[220:223], v[32:47]
	ds_read_b128 v[244:247], v176 offset:41568
	s_waitcnt lgkmcnt(7)
	v_mfma_f32_32x32x16_bf16 v[16:31], v[212:215], v[216:219], v[16:31]
	s_waitcnt lgkmcnt(6)
	v_mfma_f32_32x32x16_bf16 v[0:15], v[212:215], v[220:223], v[0:15]
	s_waitcnt lgkmcnt(0)
	s_barrier
	s_waitcnt vmcnt(6)
	s_waitcnt lgkmcnt(1)
	v_mfma_f32_32x32x16_bf16 v[112:127], v[224:227], v[240:243], v[112:127]
	ds_write_b128 v189, v[164:167]
	ds_write_b128 v189, v[128:131] offset:4608
	s_waitcnt lgkmcnt(2)
	v_mfma_f32_32x32x16_bf16 v[96:111], v[224:227], v[244:247], v[96:111]
	ds_write_b128 v189, v[132:135] offset:9216
	global_load_dwordx4 v[164:167], v190, s[42:43]
	s_waitcnt lgkmcnt(4)
	v_mfma_f32_32x32x16_bf16 v[80:95], v[228:231], v[240:243], v[80:95]
	ds_write_b128 v189, v[136:139] offset:13824
	ds_write_b128 v189, v[144:147] offset:18432
	global_load_dwordx4 v[128:131], v191, s[42:43]
	s_waitcnt lgkmcnt(5)
	v_mfma_f32_32x32x16_bf16 v[64:79], v[228:231], v[244:247], v[64:79]
	ds_write_b128 v189, v[148:151] offset:23040
	global_load_dwordx4 v[132:135], v192, s[42:43]
	s_waitcnt lgkmcnt(7)
	v_mfma_f32_32x32x16_bf16 v[48:63], v[232:235], v[240:243], v[48:63]
	s_waitcnt vmcnt(8)
	ds_write_b128 v189, v[140:143] offset:36864
	s_waitcnt vmcnt(7)
	ds_write_b128 v189, v[160:163] offset:41472
	global_load_dwordx4 v[136:139], v193, s[42:43]
	s_waitcnt lgkmcnt(8)
	v_mfma_f32_32x32x16_bf16 v[32:47], v[232:235], v[244:247], v[32:47]
	s_waitcnt vmcnt(7)
	ds_write_b128 v189, v[168:171] offset:46080
	global_load_dwordx4 v[144:147], v194, s[42:43]
	s_waitcnt lgkmcnt(10)
	v_mfma_f32_32x32x16_bf16 v[16:31], v[236:239], v[240:243], v[16:31]
	s_waitcnt vmcnt(7)
	ds_write_b128 v189, v[172:175] offset:50688
	s_waitcnt vmcnt(6)
	ds_write_b128 v189, v[152:155] offset:27648
	global_load_dwordx4 v[148:151], v195, s[42:43]
	s_waitcnt lgkmcnt(11)
	v_mfma_f32_32x32x16_bf16 v[0:15], v[236:239], v[244:247], v[0:15]
	s_waitcnt vmcnt(6)
	ds_write_b128 v189, v[156:159] offset:32256
	s_waitcnt lgkmcnt(0)
	s_barrier
	s_cmpk_lg_i32 s16, 0x780
	s_cbranch_scc1 .LBB0_1284
	ds_read_b128 v[216:219], v176 offset:36864
	ds_read_b128 v[200:203], v188
	ds_read_b128 v[220:223], v176 offset:41472
	ds_read_b128 v[204:207], v188 offset:4608
	ds_read_b128 v[208:211], v188 offset:9216
	ds_read_b128 v[212:215], v187
	s_waitcnt lgkmcnt(4)
	v_mfma_f32_32x32x16_bf16 v[112:127], v[200:203], v[216:219], v[112:127]
	ds_read_b128 v[240:243], v176 offset:36896
	s_waitcnt lgkmcnt(4)
	v_mfma_f32_32x32x16_bf16 v[96:111], v[200:203], v[220:223], v[96:111]
	ds_read_b128 v[224:227], v188 offset:32
	s_waitcnt lgkmcnt(4)
	v_mfma_f32_32x32x16_bf16 v[80:95], v[204:207], v[216:219], v[80:95]
	ds_read_b128 v[244:247], v176 offset:41504
	s_waitcnt lgkmcnt(5)
	v_mfma_f32_32x32x16_bf16 v[64:79], v[204:207], v[220:223], v[64:79]
	ds_read_b128 v[228:231], v188 offset:4640
	s_waitcnt lgkmcnt(5)
	v_mfma_f32_32x32x16_bf16 v[48:63], v[208:211], v[216:219], v[48:63]
	ds_read_b128 v[232:235], v188 offset:9248
	s_waitcnt lgkmcnt(6)
	v_mfma_f32_32x32x16_bf16 v[32:47], v[208:211], v[220:223], v[32:47]
	ds_read_b128 v[236:239], v187 offset:32
	s_waitcnt lgkmcnt(6)
	v_mfma_f32_32x32x16_bf16 v[16:31], v[212:215], v[216:219], v[16:31]
	s_waitcnt lgkmcnt(6)
	v_mfma_f32_32x32x16_bf16 v[0:15], v[212:215], v[220:223], v[0:15]
	s_waitcnt lgkmcnt(4)
	v_mfma_f32_32x32x16_bf16 v[112:127], v[224:227], v[240:243], v[112:127]
	ds_read_b128 v[200:203], v188 offset:64
	s_waitcnt lgkmcnt(4)
	v_mfma_f32_32x32x16_bf16 v[96:111], v[224:227], v[244:247], v[96:111]
	ds_read_b128 v[204:207], v188 offset:4672
	s_waitcnt lgkmcnt(4)
	v_mfma_f32_32x32x16_bf16 v[80:95], v[228:231], v[240:243], v[80:95]
	ds_read_b128 v[208:211], v188 offset:9280
	s_waitcnt lgkmcnt(5)
	v_mfma_f32_32x32x16_bf16 v[64:79], v[228:231], v[244:247], v[64:79]
	ds_read_b128 v[212:215], v187 offset:64
	s_waitcnt lgkmcnt(5)
	v_mfma_f32_32x32x16_bf16 v[48:63], v[232:235], v[240:243], v[48:63]
	ds_read_b128 v[216:219], v176 offset:36928
	s_waitcnt lgkmcnt(6)
	v_mfma_f32_32x32x16_bf16 v[32:47], v[232:235], v[244:247], v[32:47]
	ds_read_b128 v[220:223], v176 offset:41536
	s_waitcnt lgkmcnt(6)
	v_mfma_f32_32x32x16_bf16 v[16:31], v[236:239], v[240:243], v[16:31]
	s_waitcnt lgkmcnt(6)
	v_mfma_f32_32x32x16_bf16 v[0:15], v[236:239], v[244:247], v[0:15]
	s_waitcnt lgkmcnt(1)
	v_mfma_f32_32x32x16_bf16 v[112:127], v[200:203], v[216:219], v[112:127]
	ds_read_b128 v[224:227], v188 offset:96
	s_waitcnt lgkmcnt(1)
	v_mfma_f32_32x32x16_bf16 v[96:111], v[200:203], v[220:223], v[96:111]
	ds_read_b128 v[228:231], v188 offset:4704
	s_waitcnt lgkmcnt(3)
	v_mfma_f32_32x32x16_bf16 v[80:95], v[204:207], v[216:219], v[80:95]
	ds_read_b128 v[232:235], v188 offset:9312
	s_waitcnt lgkmcnt(3)
	v_mfma_f32_32x32x16_bf16 v[64:79], v[204:207], v[220:223], v[64:79]
	ds_read_b128 v[236:239], v187 offset:96
	s_waitcnt lgkmcnt(5)
	v_mfma_f32_32x32x16_bf16 v[48:63], v[208:211], v[216:219], v[48:63]
	ds_read_b128 v[240:243], v176 offset:36960
	s_waitcnt lgkmcnt(5)
	v_mfma_f32_32x32x16_bf16 v[32:47], v[208:211], v[220:223], v[32:47]
	ds_read_b128 v[244:247], v176 offset:41568
	s_waitcnt lgkmcnt(7)
	v_mfma_f32_32x32x16_bf16 v[16:31], v[212:215], v[216:219], v[16:31]
	s_waitcnt lgkmcnt(6)
	v_mfma_f32_32x32x16_bf16 v[0:15], v[212:215], v[220:223], v[0:15]
	s_waitcnt lgkmcnt(1)
	v_mfma_f32_32x32x16_bf16 v[112:127], v[224:227], v[240:243], v[112:127]
	s_waitcnt lgkmcnt(0)
	v_mfma_f32_32x32x16_bf16 v[96:111], v[224:227], v[244:247], v[96:111]
	s_waitcnt lgkmcnt(1)
	v_mfma_f32_32x32x16_bf16 v[80:95], v[228:231], v[240:243], v[80:95]
	s_waitcnt lgkmcnt(0)
	v_mfma_f32_32x32x16_bf16 v[64:79], v[228:231], v[244:247], v[64:79]
	s_waitcnt lgkmcnt(1)
	v_mfma_f32_32x32x16_bf16 v[48:63], v[232:235], v[240:243], v[48:63]
	s_waitcnt lgkmcnt(0)
	v_mfma_f32_32x32x16_bf16 v[32:47], v[232:235], v[244:247], v[32:47]
	s_waitcnt lgkmcnt(1)
	v_mfma_f32_32x32x16_bf16 v[16:31], v[236:239], v[240:243], v[16:31]
	s_waitcnt lgkmcnt(0)
	v_mfma_f32_32x32x16_bf16 v[0:15], v[236:239], v[244:247], v[0:15]
	s_waitcnt vmcnt(0)
	s_mul_i32 s41, s12, 0x1240
	s_add_u32 s42, s30, s41
	s_addc_u32 s43, s31, 0
	s_lshl_b32 s41, s8, 1
	s_add_u32 s42, s42, s41
	s_addc_u32 s43, s43, 0
	s_add_u32 s42, s42, 0x7157900
	s_addc_u32 s43, s43, 0
	v_and_b32_e32 v131, 15, v182
	v_lshrrev_b32_e32 v172, 4, v182
	v_lshl_add_u32 v130, v131, 3, s8
	s_movk_i32 s41, 0x920
	v_cmp_gt_u32_e64 s[44:45], s41, v130
	v_mul_u32_u24_e32 v164, 0x1240, v172
	v_lshl_add_u32 v164, v131, 4, v164
	v_add_u32_e32 v165, 0x12400, v164
	v_add_u32_e32 v166, 0x24800, v164
	v_add_u32_e32 v167, 0x36c00, v164
	v_add_u32_e32 v168, 0x92000, v164
	v_add_u32_e32 v169, 0xa4400, v164
	v_add_u32_e32 v170, 0xb6800, v164
	v_add_u32_e32 v171, 0xc8c00, v164
	v_mul_u32_u24_e32 v129, 0x110, v172
	v_lshl_add_u32 v129, v131, 4, v129
	v_lshrrev_b32_e32 v131, 7, v182
	v_bfe_u32 v172, v182, 5, 1
	v_lshlrev_b32_e32 v131, 6, v131
	v_lshl_or_b32 v131, v172, 2, v131
	v_mul_u32_u24_e32 v131, 136, v131
	v_and_b32_e32 v172, 0x5f, v182
	v_add_lshl_u32 v128, v131, v172, 1
	s_barrier
	v_cvt_pk_bf16_f32 v112, v112, v113
	v_cvt_pk_bf16_f32 v114, v114, v115
	v_cvt_pk_bf16_f32 v116, v116, v117
	v_cvt_pk_bf16_f32 v118, v118, v119
	v_cvt_pk_bf16_f32 v120, v120, v121
	v_cvt_pk_bf16_f32 v122, v122, v123
	v_cvt_pk_bf16_f32 v124, v124, v125
	v_cvt_pk_bf16_f32 v126, v126, v127
	v_cvt_pk_bf16_f32 v96, v96, v97
	v_cvt_pk_bf16_f32 v98, v98, v99
	v_cvt_pk_bf16_f32 v100, v100, v101
	v_cvt_pk_bf16_f32 v102, v102, v103
	v_cvt_pk_bf16_f32 v104, v104, v105
	v_cvt_pk_bf16_f32 v106, v106, v107
	v_cvt_pk_bf16_f32 v108, v108, v109
	v_cvt_pk_bf16_f32 v110, v110, v111
	v_cvt_pk_bf16_f32 v80, v80, v81
	v_cvt_pk_bf16_f32 v82, v82, v83
	v_cvt_pk_bf16_f32 v84, v84, v85
	v_cvt_pk_bf16_f32 v86, v86, v87
	v_cvt_pk_bf16_f32 v88, v88, v89
	v_cvt_pk_bf16_f32 v90, v90, v91
	v_cvt_pk_bf16_f32 v92, v92, v93
	v_cvt_pk_bf16_f32 v94, v94, v95
	v_cvt_pk_bf16_f32 v64, v64, v65
	v_cvt_pk_bf16_f32 v66, v66, v67
	v_cvt_pk_bf16_f32 v68, v68, v69
	v_cvt_pk_bf16_f32 v70, v70, v71
	v_cvt_pk_bf16_f32 v72, v72, v73
	v_cvt_pk_bf16_f32 v74, v74, v75
	v_cvt_pk_bf16_f32 v76, v76, v77
	v_cvt_pk_bf16_f32 v78, v78, v79
	ds_write_b16 v128, v112
	ds_write_b16_d16_hi v128, v112 offset:272
	ds_write_b16 v128, v114 offset:544
	ds_write_b16_d16_hi v128, v114 offset:816
	ds_write_b16 v128, v116 offset:2176
	ds_write_b16_d16_hi v128, v116 offset:2448
	ds_write_b16 v128, v118 offset:2720
	ds_write_b16_d16_hi v128, v118 offset:2992
	ds_write_b16 v128, v120 offset:4352
	ds_write_b16_d16_hi v128, v120 offset:4624
	ds_write_b16 v128, v122 offset:4896
	ds_write_b16_d16_hi v128, v122 offset:5168
	ds_write_b16 v128, v124 offset:6528
	ds_write_b16_d16_hi v128, v124 offset:6800
	ds_write_b16 v128, v126 offset:7072
	ds_write_b16_d16_hi v128, v126 offset:7344
	ds_write_b16 v128, v96 offset:64
	ds_write_b16_d16_hi v128, v96 offset:336
	ds_write_b16 v128, v98 offset:608
	ds_write_b16_d16_hi v128, v98 offset:880
	ds_write_b16 v128, v100 offset:2240
	ds_write_b16_d16_hi v128, v100 offset:2512
	ds_write_b16 v128, v102 offset:2784
	ds_write_b16_d16_hi v128, v102 offset:3056
	ds_write_b16 v128, v104 offset:4416
	ds_write_b16_d16_hi v128, v104 offset:4688
	ds_write_b16 v128, v106 offset:4960
	ds_write_b16_d16_hi v128, v106 offset:5232
	ds_write_b16 v128, v108 offset:6592
	ds_write_b16_d16_hi v128, v108 offset:6864
	ds_write_b16 v128, v110 offset:7136
	ds_write_b16_d16_hi v128, v110 offset:7408
	ds_write_b16 v128, v80 offset:8704
	ds_write_b16_d16_hi v128, v80 offset:8976
	ds_write_b16 v128, v82 offset:9248
	ds_write_b16_d16_hi v128, v82 offset:9520
	ds_write_b16 v128, v84 offset:10880
	ds_write_b16_d16_hi v128, v84 offset:11152
	ds_write_b16 v128, v86 offset:11424
	ds_write_b16_d16_hi v128, v86 offset:11696
	ds_write_b16 v128, v88 offset:13056
	ds_write_b16_d16_hi v128, v88 offset:13328
	ds_write_b16 v128, v90 offset:13600
	ds_write_b16_d16_hi v128, v90 offset:13872
	ds_write_b16 v128, v92 offset:15232
	ds_write_b16_d16_hi v128, v92 offset:15504
	ds_write_b16 v128, v94 offset:15776
	ds_write_b16_d16_hi v128, v94 offset:16048
	ds_write_b16 v128, v64 offset:8768
	ds_write_b16_d16_hi v128, v64 offset:9040
	ds_write_b16 v128, v66 offset:9312
	ds_write_b16_d16_hi v128, v66 offset:9584
	ds_write_b16 v128, v68 offset:10944
	ds_write_b16_d16_hi v128, v68 offset:11216
	ds_write_b16 v128, v70 offset:11488
	ds_write_b16_d16_hi v128, v70 offset:11760
	ds_write_b16 v128, v72 offset:13120
	ds_write_b16_d16_hi v128, v72 offset:13392
	ds_write_b16 v128, v74 offset:13664
	ds_write_b16_d16_hi v128, v74 offset:13936
	ds_write_b16 v128, v76 offset:15296
	ds_write_b16_d16_hi v128, v76 offset:15568
	ds_write_b16 v128, v78 offset:15840
	ds_write_b16_d16_hi v128, v78 offset:16112
	s_waitcnt lgkmcnt(0)
	s_barrier
	ds_read_b128 v[132:135], v129
	ds_read_b128 v[136:139], v129 offset:4352
	ds_read_b128 v[140:143], v129 offset:8704
	ds_read_b128 v[144:147], v129 offset:13056
	ds_read_b128 v[148:151], v129 offset:17408
	ds_read_b128 v[152:155], v129 offset:21760
	ds_read_b128 v[156:159], v129 offset:26112
	ds_read_b128 v[160:163], v129 offset:30464
	v_cvt_pk_bf16_f32 v48, v48, v49
	v_cvt_pk_bf16_f32 v50, v50, v51
	v_cvt_pk_bf16_f32 v52, v52, v53
	v_cvt_pk_bf16_f32 v54, v54, v55
	v_cvt_pk_bf16_f32 v56, v56, v57
	v_cvt_pk_bf16_f32 v58, v58, v59
	v_cvt_pk_bf16_f32 v60, v60, v61
	v_cvt_pk_bf16_f32 v62, v62, v63
	v_cvt_pk_bf16_f32 v32, v32, v33
	v_cvt_pk_bf16_f32 v34, v34, v35
	v_cvt_pk_bf16_f32 v36, v36, v37
	v_cvt_pk_bf16_f32 v38, v38, v39
	v_cvt_pk_bf16_f32 v40, v40, v41
	v_cvt_pk_bf16_f32 v42, v42, v43
	v_cvt_pk_bf16_f32 v44, v44, v45
	v_cvt_pk_bf16_f32 v46, v46, v47
	v_cvt_pk_bf16_f32 v16, v16, v17
	v_cvt_pk_bf16_f32 v18, v18, v19
	v_cvt_pk_bf16_f32 v20, v20, v21
	v_cvt_pk_bf16_f32 v22, v22, v23
	v_cvt_pk_bf16_f32 v24, v24, v25
	v_cvt_pk_bf16_f32 v26, v26, v27
	v_cvt_pk_bf16_f32 v28, v28, v29
	v_cvt_pk_bf16_f32 v30, v30, v31
	v_cvt_pk_bf16_f32 v0, v0, v1
	v_cvt_pk_bf16_f32 v2, v2, v3
	v_cvt_pk_bf16_f32 v4, v4, v5
	v_cvt_pk_bf16_f32 v6, v6, v7
	v_cvt_pk_bf16_f32 v8, v8, v9
	v_cvt_pk_bf16_f32 v10, v10, v11
	v_cvt_pk_bf16_f32 v12, v12, v13
	v_cvt_pk_bf16_f32 v14, v14, v15
	s_and_saveexec_b64 s[46:47], s[44:45]
	s_waitcnt lgkmcnt(7)
	global_store_dwordx4 v164, v[132:135], s[42:43]
	s_waitcnt lgkmcnt(6)
	global_store_dwordx4 v165, v[136:139], s[42:43]
	s_waitcnt lgkmcnt(5)
	global_store_dwordx4 v166, v[140:143], s[42:43]
	s_waitcnt lgkmcnt(4)
	global_store_dwordx4 v167, v[144:147], s[42:43]
	s_waitcnt lgkmcnt(3)
	global_store_dwordx4 v168, v[148:151], s[42:43]
	s_waitcnt lgkmcnt(2)
	global_store_dwordx4 v169, v[152:155], s[42:43]
	s_waitcnt lgkmcnt(1)
	global_store_dwordx4 v170, v[156:159], s[42:43]
	s_waitcnt lgkmcnt(0)
	global_store_dwordx4 v171, v[160:163], s[42:43]
	s_or_b64 exec, exec, s[46:47]
	s_barrier
	ds_write_b16 v128, v48
	ds_write_b16_d16_hi v128, v48 offset:272
	ds_write_b16 v128, v50 offset:544
	ds_write_b16_d16_hi v128, v50 offset:816
	ds_write_b16 v128, v52 offset:2176
	ds_write_b16_d16_hi v128, v52 offset:2448
	ds_write_b16 v128, v54 offset:2720
	ds_write_b16_d16_hi v128, v54 offset:2992
	ds_write_b16 v128, v56 offset:4352
	ds_write_b16_d16_hi v128, v56 offset:4624
	ds_write_b16 v128, v58 offset:4896
	ds_write_b16_d16_hi v128, v58 offset:5168
	ds_write_b16 v128, v60 offset:6528
	ds_write_b16_d16_hi v128, v60 offset:6800
	ds_write_b16 v128, v62 offset:7072
	ds_write_b16_d16_hi v128, v62 offset:7344
	ds_write_b16 v128, v32 offset:64
	ds_write_b16_d16_hi v128, v32 offset:336
	ds_write_b16 v128, v34 offset:608
	ds_write_b16_d16_hi v128, v34 offset:880
	ds_write_b16 v128, v36 offset:2240
	ds_write_b16_d16_hi v128, v36 offset:2512
	ds_write_b16 v128, v38 offset:2784
	ds_write_b16_d16_hi v128, v38 offset:3056
	ds_write_b16 v128, v40 offset:4416
	ds_write_b16_d16_hi v128, v40 offset:4688
	ds_write_b16 v128, v42 offset:4960
	ds_write_b16_d16_hi v128, v42 offset:5232
	ds_write_b16 v128, v44 offset:6592
	ds_write_b16_d16_hi v128, v44 offset:6864
	ds_write_b16 v128, v46 offset:7136
	ds_write_b16_d16_hi v128, v46 offset:7408
	ds_write_b16 v128, v16 offset:8704
	ds_write_b16_d16_hi v128, v16 offset:8976
	ds_write_b16 v128, v18 offset:9248
	ds_write_b16_d16_hi v128, v18 offset:9520
	ds_write_b16 v128, v20 offset:10880
	ds_write_b16_d16_hi v128, v20 offset:11152
	ds_write_b16 v128, v22 offset:11424
	ds_write_b16_d16_hi v128, v22 offset:11696
	ds_write_b16 v128, v24 offset:13056
	ds_write_b16_d16_hi v128, v24 offset:13328
	ds_write_b16 v128, v26 offset:13600
	ds_write_b16_d16_hi v128, v26 offset:13872
	ds_write_b16 v128, v28 offset:15232
	ds_write_b16_d16_hi v128, v28 offset:15504
	ds_write_b16 v128, v30 offset:15776
	ds_write_b16_d16_hi v128, v30 offset:16048
	ds_write_b16 v128, v0 offset:8768
	ds_write_b16_d16_hi v128, v0 offset:9040
	ds_write_b16 v128, v2 offset:9312
	ds_write_b16_d16_hi v128, v2 offset:9584
	ds_write_b16 v128, v4 offset:10944
	ds_write_b16_d16_hi v128, v4 offset:11216
	ds_write_b16 v128, v6 offset:11488
	ds_write_b16_d16_hi v128, v6 offset:11760
	ds_write_b16 v128, v8 offset:13120
	ds_write_b16_d16_hi v128, v8 offset:13392
	ds_write_b16 v128, v10 offset:13664
	ds_write_b16_d16_hi v128, v10 offset:13936
	ds_write_b16 v128, v12 offset:15296
	ds_write_b16_d16_hi v128, v12 offset:15568
	ds_write_b16 v128, v14 offset:15840
	ds_write_b16_d16_hi v128, v14 offset:16112
	s_waitcnt lgkmcnt(0)
	s_barrier
	ds_read_b128 v[132:135], v129
	ds_read_b128 v[136:139], v129 offset:4352
	ds_read_b128 v[140:143], v129 offset:8704
	ds_read_b128 v[144:147], v129 offset:13056
	ds_read_b128 v[148:151], v129 offset:17408
	ds_read_b128 v[152:155], v129 offset:21760
	ds_read_b128 v[156:159], v129 offset:26112
	ds_read_b128 v[160:163], v129 offset:30464
	v_add_u32_e32 v164, 0x49000, v164
	v_add_u32_e32 v165, 0x49000, v165
	v_add_u32_e32 v166, 0x49000, v166
	v_add_u32_e32 v167, 0x49000, v167
	v_add_u32_e32 v168, 0x49000, v168
	v_add_u32_e32 v169, 0x49000, v169
	v_add_u32_e32 v170, 0x49000, v170
	v_add_u32_e32 v171, 0x49000, v171
	s_and_saveexec_b64 s[46:47], s[44:45]
	s_waitcnt lgkmcnt(7)
	global_store_dwordx4 v164, v[132:135], s[42:43]
	s_waitcnt lgkmcnt(6)
	global_store_dwordx4 v165, v[136:139], s[42:43]
	s_waitcnt lgkmcnt(5)
	global_store_dwordx4 v166, v[140:143], s[42:43]
	s_waitcnt lgkmcnt(4)
	global_store_dwordx4 v167, v[144:147], s[42:43]
	s_waitcnt lgkmcnt(3)
	global_store_dwordx4 v168, v[148:151], s[42:43]
	s_waitcnt lgkmcnt(2)
	global_store_dwordx4 v169, v[152:155], s[42:43]
	s_waitcnt lgkmcnt(1)
	global_store_dwordx4 v170, v[156:159], s[42:43]
	s_waitcnt lgkmcnt(0)
	global_store_dwordx4 v171, v[160:163], s[42:43]
	s_or_b64 exec, exec, s[46:47]
	s_branch .LBB0_1281

.LBB0_1977:
	ds_read_b128 v[216:219], v188 offset:36864
	ds_read_b128 v[200:203], v187
	ds_read_b128 v[220:223], v188 offset:41472
	ds_read_b128 v[204:207], v187 offset:4608
	ds_read_b128 v[208:211], v187 offset:9216
	ds_read_b128 v[212:215], v176
	s_waitcnt lgkmcnt(4)
	v_mfma_f32_32x32x16_bf16 v[112:127], v[200:203], v[216:219], v[112:127]
	ds_read_b128 v[240:243], v188 offset:36896
	global_load_dwordx4 v[152:155], v190, s[40:41]
	s_waitcnt lgkmcnt(4)
	v_mfma_f32_32x32x16_bf16 v[96:111], v[200:203], v[220:223], v[96:111]
	ds_read_b128 v[224:227], v187 offset:32
	global_load_dwordx4 v[164:167], v191, s[40:41]
	s_waitcnt lgkmcnt(4)
	v_mfma_f32_32x32x16_bf16 v[80:95], v[204:207], v[216:219], v[80:95]
	ds_read_b128 v[244:247], v188 offset:41504
	global_load_dwordx4 v[168:171], v192, s[40:41]
	s_waitcnt lgkmcnt(5)
	v_mfma_f32_32x32x16_bf16 v[64:79], v[204:207], v[220:223], v[64:79]
	ds_read_b128 v[228:231], v187 offset:4640
	global_load_dwordx4 v[172:175], v193, s[40:41]
	s_waitcnt lgkmcnt(5)
	v_mfma_f32_32x32x16_bf16 v[48:63], v[208:211], v[216:219], v[48:63]
	ds_read_b128 v[232:235], v187 offset:9248
	global_load_dwordx4 v[148:151], v196, s[38:39]
	s_waitcnt lgkmcnt(6)
	v_mfma_f32_32x32x16_bf16 v[32:47], v[208:211], v[220:223], v[32:47]
	ds_read_b128 v[236:239], v176 offset:32
	global_load_dwordx4 v[156:159], v197, s[38:39]
	s_add_u32 s38, s38, 0x80
	s_addc_u32 s39, s39, 0
	s_add_u32 s40, s40, 0x80
	s_addc_u32 s41, s41, 0
	s_add_u32 s12, s12, 0x80
	s_waitcnt lgkmcnt(6)
	v_mfma_f32_32x32x16_bf16 v[16:31], v[212:215], v[216:219], v[16:31]
	s_waitcnt lgkmcnt(6)
	v_mfma_f32_32x32x16_bf16 v[0:15], v[212:215], v[220:223], v[0:15]
	s_waitcnt lgkmcnt(4)
	v_mfma_f32_32x32x16_bf16 v[112:127], v[224:227], v[240:243], v[112:127]
	ds_read_b128 v[200:203], v187 offset:64
	s_waitcnt lgkmcnt(4)
	v_mfma_f32_32x32x16_bf16 v[96:111], v[224:227], v[244:247], v[96:111]
	ds_read_b128 v[204:207], v187 offset:4672
	s_waitcnt lgkmcnt(4)
	v_mfma_f32_32x32x16_bf16 v[80:95], v[228:231], v[240:243], v[80:95]
	ds_read_b128 v[208:211], v187 offset:9280
	s_waitcnt lgkmcnt(5)
	v_mfma_f32_32x32x16_bf16 v[64:79], v[228:231], v[244:247], v[64:79]
	ds_read_b128 v[212:215], v176 offset:64
	s_waitcnt lgkmcnt(5)
	v_mfma_f32_32x32x16_bf16 v[48:63], v[232:235], v[240:243], v[48:63]
	ds_read_b128 v[216:219], v188 offset:36928
	s_waitcnt lgkmcnt(6)
	v_mfma_f32_32x32x16_bf16 v[32:47], v[232:235], v[244:247], v[32:47]
	ds_read_b128 v[220:223], v188 offset:41536
	s_waitcnt lgkmcnt(6)
	v_mfma_f32_32x32x16_bf16 v[16:31], v[236:239], v[240:243], v[16:31]
	s_waitcnt lgkmcnt(6)
	v_mfma_f32_32x32x16_bf16 v[0:15], v[236:239], v[244:247], v[0:15]
	s_waitcnt lgkmcnt(1)
	v_mfma_f32_32x32x16_bf16 v[112:127], v[200:203], v[216:219], v[112:127]
	ds_read_b128 v[224:227], v187 offset:96
	s_waitcnt lgkmcnt(1)
	v_mfma_f32_32x32x16_bf16 v[96:111], v[200:203], v[220:223], v[96:111]
	ds_read_b128 v[228:231], v187 offset:4704
	s_waitcnt lgkmcnt(3)
	v_mfma_f32_32x32x16_bf16 v[80:95], v[204:207], v[216:219], v[80:95]
	ds_read_b128 v[232:235], v187 offset:9312
	s_waitcnt lgkmcnt(3)
	v_mfma_f32_32x32x16_bf16 v[64:79], v[204:207], v[220:223], v[64:79]
	ds_read_b128 v[236:239], v176 offset:96
	s_waitcnt lgkmcnt(5)
	v_mfma_f32_32x32x16_bf16 v[48:63], v[208:211], v[216:219], v[48:63]
	ds_read_b128 v[240:243], v188 offset:36960
	s_waitcnt lgkmcnt(5)
	v_mfma_f32_32x32x16_bf16 v[32:47], v[208:211], v[220:223], v[32:47]
	ds_read_b128 v[244:247], v188 offset:41568
	s_waitcnt lgkmcnt(7)
	v_mfma_f32_32x32x16_bf16 v[16:31], v[212:215], v[216:219], v[16:31]
	s_waitcnt lgkmcnt(6)
	v_mfma_f32_32x32x16_bf16 v[0:15], v[212:215], v[220:223], v[0:15]
	s_waitcnt lgkmcnt(0)
	s_barrier
	s_waitcnt vmcnt(6)
	s_waitcnt lgkmcnt(1)
	v_mfma_f32_32x32x16_bf16 v[112:127], v[224:227], v[240:243], v[112:127]
	ds_write_b128 v189, v[160:163]
	ds_write_b128 v189, v[128:131] offset:4608
	s_waitcnt lgkmcnt(2)
	v_mfma_f32_32x32x16_bf16 v[96:111], v[224:227], v[244:247], v[96:111]
	ds_write_b128 v189, v[132:135] offset:9216
	global_load_dwordx4 v[160:163], v190, s[38:39]
	s_waitcnt lgkmcnt(4)
	v_mfma_f32_32x32x16_bf16 v[80:95], v[228:231], v[240:243], v[80:95]
	ds_write_b128 v189, v[136:139] offset:13824
	ds_write_b128 v189, v[140:143] offset:18432
	global_load_dwordx4 v[128:131], v191, s[38:39]
	s_waitcnt lgkmcnt(5)
	v_mfma_f32_32x32x16_bf16 v[64:79], v[228:231], v[244:247], v[64:79]
	ds_write_b128 v189, v[144:147] offset:23040
	global_load_dwordx4 v[132:135], v192, s[38:39]
	s_waitcnt lgkmcnt(7)
	v_mfma_f32_32x32x16_bf16 v[48:63], v[232:235], v[240:243], v[48:63]
	s_waitcnt vmcnt(8)
	ds_write_b128 v189, v[152:155] offset:36864
	s_waitcnt vmcnt(7)
	ds_write_b128 v189, v[164:167] offset:41472
	global_load_dwordx4 v[136:139], v193, s[38:39]
	s_waitcnt lgkmcnt(8)
	v_mfma_f32_32x32x16_bf16 v[32:47], v[232:235], v[244:247], v[32:47]
	s_waitcnt vmcnt(7)
	ds_write_b128 v189, v[168:171] offset:46080
	global_load_dwordx4 v[140:143], v194, s[38:39]
	s_waitcnt lgkmcnt(10)
	v_mfma_f32_32x32x16_bf16 v[16:31], v[236:239], v[240:243], v[16:31]
	s_waitcnt vmcnt(7)
	ds_write_b128 v189, v[172:175] offset:50688
	s_waitcnt vmcnt(6)
	ds_write_b128 v189, v[148:151] offset:27648
	global_load_dwordx4 v[144:147], v195, s[38:39]
	s_waitcnt lgkmcnt(11)
	v_mfma_f32_32x32x16_bf16 v[0:15], v[236:239], v[244:247], v[0:15]
	s_waitcnt vmcnt(6)
	ds_write_b128 v189, v[156:159] offset:32256
	s_waitcnt lgkmcnt(0)
	s_barrier
	s_cmpk_lg_i32 s12, 0x780
	s_cbranch_scc1 .LBB0_1977
	ds_read_b128 v[216:219], v188 offset:36864
	ds_read_b128 v[200:203], v187
	ds_read_b128 v[220:223], v188 offset:41472
	ds_read_b128 v[204:207], v187 offset:4608
	ds_read_b128 v[208:211], v187 offset:9216
	ds_read_b128 v[212:215], v176
	s_waitcnt lgkmcnt(4)
	v_mfma_f32_32x32x16_bf16 v[112:127], v[200:203], v[216:219], v[112:127]
	ds_read_b128 v[240:243], v188 offset:36896
	s_waitcnt lgkmcnt(4)
	v_mfma_f32_32x32x16_bf16 v[96:111], v[200:203], v[220:223], v[96:111]
	ds_read_b128 v[224:227], v187 offset:32
	s_waitcnt lgkmcnt(4)
	v_mfma_f32_32x32x16_bf16 v[80:95], v[204:207], v[216:219], v[80:95]
	ds_read_b128 v[244:247], v188 offset:41504
	s_waitcnt lgkmcnt(5)
	v_mfma_f32_32x32x16_bf16 v[64:79], v[204:207], v[220:223], v[64:79]
	ds_read_b128 v[228:231], v187 offset:4640
	s_waitcnt lgkmcnt(5)
	v_mfma_f32_32x32x16_bf16 v[48:63], v[208:211], v[216:219], v[48:63]
	ds_read_b128 v[232:235], v187 offset:9248
	s_waitcnt lgkmcnt(6)
	v_mfma_f32_32x32x16_bf16 v[32:47], v[208:211], v[220:223], v[32:47]
	ds_read_b128 v[236:239], v176 offset:32
	s_waitcnt lgkmcnt(6)
	v_mfma_f32_32x32x16_bf16 v[16:31], v[212:215], v[216:219], v[16:31]
	s_waitcnt lgkmcnt(6)
	v_mfma_f32_32x32x16_bf16 v[0:15], v[212:215], v[220:223], v[0:15]
	s_waitcnt lgkmcnt(4)
	v_mfma_f32_32x32x16_bf16 v[112:127], v[224:227], v[240:243], v[112:127]
	ds_read_b128 v[200:203], v187 offset:64
	s_waitcnt lgkmcnt(4)
	v_mfma_f32_32x32x16_bf16 v[96:111], v[224:227], v[244:247], v[96:111]
	ds_read_b128 v[204:207], v187 offset:4672
	s_waitcnt lgkmcnt(4)
	v_mfma_f32_32x32x16_bf16 v[80:95], v[228:231], v[240:243], v[80:95]
	ds_read_b128 v[208:211], v187 offset:9280
	s_waitcnt lgkmcnt(5)
	v_mfma_f32_32x32x16_bf16 v[64:79], v[228:231], v[244:247], v[64:79]
	ds_read_b128 v[212:215], v176 offset:64
	s_waitcnt lgkmcnt(5)
	v_mfma_f32_32x32x16_bf16 v[48:63], v[232:235], v[240:243], v[48:63]
	ds_read_b128 v[216:219], v188 offset:36928
	s_waitcnt lgkmcnt(6)
	v_mfma_f32_32x32x16_bf16 v[32:47], v[232:235], v[244:247], v[32:47]
	ds_read_b128 v[220:223], v188 offset:41536
	s_waitcnt lgkmcnt(6)
	v_mfma_f32_32x32x16_bf16 v[16:31], v[236:239], v[240:243], v[16:31]
	s_waitcnt lgkmcnt(6)
	v_mfma_f32_32x32x16_bf16 v[0:15], v[236:239], v[244:247], v[0:15]
	s_waitcnt lgkmcnt(1)
	v_mfma_f32_32x32x16_bf16 v[112:127], v[200:203], v[216:219], v[112:127]
	ds_read_b128 v[224:227], v187 offset:96
	s_waitcnt lgkmcnt(1)
	v_mfma_f32_32x32x16_bf16 v[96:111], v[200:203], v[220:223], v[96:111]
	ds_read_b128 v[228:231], v187 offset:4704
	s_waitcnt lgkmcnt(3)
	v_mfma_f32_32x32x16_bf16 v[80:95], v[204:207], v[216:219], v[80:95]
	ds_read_b128 v[232:235], v187 offset:9312
	s_waitcnt lgkmcnt(3)
	v_mfma_f32_32x32x16_bf16 v[64:79], v[204:207], v[220:223], v[64:79]
	ds_read_b128 v[236:239], v176 offset:96
	s_waitcnt lgkmcnt(5)
	v_mfma_f32_32x32x16_bf16 v[48:63], v[208:211], v[216:219], v[48:63]
	ds_read_b128 v[240:243], v188 offset:36960
	s_waitcnt lgkmcnt(5)
	v_mfma_f32_32x32x16_bf16 v[32:47], v[208:211], v[220:223], v[32:47]
	ds_read_b128 v[244:247], v188 offset:41568
	s_waitcnt lgkmcnt(7)
	v_mfma_f32_32x32x16_bf16 v[16:31], v[212:215], v[216:219], v[16:31]
	s_waitcnt lgkmcnt(6)
	v_mfma_f32_32x32x16_bf16 v[0:15], v[212:215], v[220:223], v[0:15]
	s_waitcnt lgkmcnt(1)
	v_mfma_f32_32x32x16_bf16 v[112:127], v[224:227], v[240:243], v[112:127]
	s_waitcnt lgkmcnt(0)
	v_mfma_f32_32x32x16_bf16 v[96:111], v[224:227], v[244:247], v[96:111]
	s_waitcnt lgkmcnt(1)
	v_mfma_f32_32x32x16_bf16 v[80:95], v[228:231], v[240:243], v[80:95]
	s_waitcnt lgkmcnt(0)
	v_mfma_f32_32x32x16_bf16 v[64:79], v[228:231], v[244:247], v[64:79]
	s_waitcnt lgkmcnt(1)
	v_mfma_f32_32x32x16_bf16 v[48:63], v[232:235], v[240:243], v[48:63]
	s_waitcnt lgkmcnt(0)
	v_mfma_f32_32x32x16_bf16 v[32:47], v[232:235], v[244:247], v[32:47]
	s_waitcnt lgkmcnt(1)
	v_mfma_f32_32x32x16_bf16 v[16:31], v[236:239], v[240:243], v[16:31]
	s_waitcnt lgkmcnt(0)
	v_mfma_f32_32x32x16_bf16 v[0:15], v[236:239], v[244:247], v[0:15]
	s_waitcnt vmcnt(0)
	s_mul_i32 s42, s6, 0x2000
	s_add_u32 s44, s30, s42
	s_addc_u32 s45, s31, 0
	s_lshl_b32 s42, s58, 1
	s_add_u32 s44, s44, s42
	s_addc_u32 s45, s45, 0
	s_add_u32 s44, s44, 0x7157900
	s_addc_u32 s45, s45, 0
	s_mov_b32 s43, 1
	v_max_f32_e32 v112, 0, v112
	v_max_f32_e32 v113, 0, v113
	v_mul_f32_e32 v112, v112, v112
	v_mul_f32_e32 v113, v113, v113
	v_cvt_pk_bf16_f32 v190, v112, v113
	v_max_f32_e32 v114, 0, v114
	v_max_f32_e32 v115, 0, v115
	v_mul_f32_e32 v114, v114, v114
	v_mul_f32_e32 v115, v115, v115
	v_cvt_pk_bf16_f32 v191, v114, v115
	v_max_f32_e32 v116, 0, v116
	v_max_f32_e32 v117, 0, v117
	v_mul_f32_e32 v116, v116, v116
	v_mul_f32_e32 v117, v117, v117
	v_cvt_pk_bf16_f32 v192, v116, v117
	v_max_f32_e32 v118, 0, v118
	v_max_f32_e32 v119, 0, v119
	v_mul_f32_e32 v118, v118, v118
	v_mul_f32_e32 v119, v119, v119
	v_cvt_pk_bf16_f32 v193, v118, v119
	v_max_f32_e32 v120, 0, v120
	v_max_f32_e32 v121, 0, v121
	v_mul_f32_e32 v120, v120, v120
	v_mul_f32_e32 v121, v121, v121
	v_cvt_pk_bf16_f32 v194, v120, v121
	v_max_f32_e32 v122, 0, v122
	v_max_f32_e32 v123, 0, v123
	v_mul_f32_e32 v122, v122, v122
	v_mul_f32_e32 v123, v123, v123
	v_cvt_pk_bf16_f32 v195, v122, v123
	v_max_f32_e32 v124, 0, v124
	v_max_f32_e32 v125, 0, v125
	v_mul_f32_e32 v124, v124, v124
	v_mul_f32_e32 v125, v125, v125
	v_cvt_pk_bf16_f32 v196, v124, v125
	v_max_f32_e32 v126, 0, v126
	v_max_f32_e32 v127, 0, v127
	v_mul_f32_e32 v126, v126, v126
	v_mul_f32_e32 v127, v127, v127
	v_cvt_pk_bf16_f32 v197, v126, v127
	v_max_f32_e32 v96, 0, v96
	v_max_f32_e32 v97, 0, v97
	v_mul_f32_e32 v96, v96, v96
	v_mul_f32_e32 v97, v97, v97
	v_cvt_pk_bf16_f32 v198, v96, v97
	v_max_f32_e32 v98, 0, v98
	v_max_f32_e32 v99, 0, v99
	v_mul_f32_e32 v98, v98, v98
	v_mul_f32_e32 v99, v99, v99
	v_cvt_pk_bf16_f32 v199, v98, v99
	v_max_f32_e32 v100, 0, v100
	v_max_f32_e32 v101, 0, v101
	v_mul_f32_e32 v100, v100, v100
	v_mul_f32_e32 v101, v101, v101
	v_cvt_pk_bf16_f32 v200, v100, v101
	v_max_f32_e32 v102, 0, v102
	v_max_f32_e32 v103, 0, v103
	v_mul_f32_e32 v102, v102, v102
	v_mul_f32_e32 v103, v103, v103
	v_cvt_pk_bf16_f32 v201, v102, v103
	v_max_f32_e32 v104, 0, v104
	v_max_f32_e32 v105, 0, v105
	v_mul_f32_e32 v104, v104, v104
	v_mul_f32_e32 v105, v105, v105
	v_cvt_pk_bf16_f32 v202, v104, v105
	v_max_f32_e32 v106, 0, v106
	v_max_f32_e32 v107, 0, v107
	v_mul_f32_e32 v106, v106, v106
	v_mul_f32_e32 v107, v107, v107
	v_cvt_pk_bf16_f32 v203, v106, v107
	v_max_f32_e32 v108, 0, v108
	v_max_f32_e32 v109, 0, v109
	v_mul_f32_e32 v108, v108, v108
	v_mul_f32_e32 v109, v109, v109
	v_cvt_pk_bf16_f32 v204, v108, v109
	v_max_f32_e32 v110, 0, v110
	v_max_f32_e32 v111, 0, v111
	v_mul_f32_e32 v110, v110, v110
	v_mul_f32_e32 v111, v111, v111
	v_cvt_pk_bf16_f32 v205, v110, v111
	v_max_f32_e32 v80, 0, v80
	v_max_f32_e32 v81, 0, v81
	v_mul_f32_e32 v80, v80, v80
	v_mul_f32_e32 v81, v81, v81
	v_cvt_pk_bf16_f32 v206, v80, v81
	v_max_f32_e32 v82, 0, v82
	v_max_f32_e32 v83, 0, v83
	v_mul_f32_e32 v82, v82, v82
	v_mul_f32_e32 v83, v83, v83
	v_cvt_pk_bf16_f32 v207, v82, v83
	v_max_f32_e32 v84, 0, v84
	v_max_f32_e32 v85, 0, v85
	v_mul_f32_e32 v84, v84, v84
	v_mul_f32_e32 v85, v85, v85
	v_cvt_pk_bf16_f32 v208, v84, v85
	v_max_f32_e32 v86, 0, v86
	v_max_f32_e32 v87, 0, v87
	v_mul_f32_e32 v86, v86, v86
	v_mul_f32_e32 v87, v87, v87
	v_cvt_pk_bf16_f32 v209, v86, v87
	v_max_f32_e32 v88, 0, v88
	v_max_f32_e32 v89, 0, v89
	v_mul_f32_e32 v88, v88, v88
	v_mul_f32_e32 v89, v89, v89
	v_cvt_pk_bf16_f32 v210, v88, v89
	v_max_f32_e32 v90, 0, v90
	v_max_f32_e32 v91, 0, v91
	v_mul_f32_e32 v90, v90, v90
	v_mul_f32_e32 v91, v91, v91
	v_cvt_pk_bf16_f32 v211, v90, v91
	v_max_f32_e32 v92, 0, v92
	v_max_f32_e32 v93, 0, v93
	v_mul_f32_e32 v92, v92, v92
	v_mul_f32_e32 v93, v93, v93
	v_cvt_pk_bf16_f32 v212, v92, v93
	v_max_f32_e32 v94, 0, v94
	v_max_f32_e32 v95, 0, v95
	v_mul_f32_e32 v94, v94, v94
	v_mul_f32_e32 v95, v95, v95
	v_cvt_pk_bf16_f32 v213, v94, v95
	v_max_f32_e32 v64, 0, v64
	v_max_f32_e32 v65, 0, v65
	v_mul_f32_e32 v64, v64, v64
	v_mul_f32_e32 v65, v65, v65
	v_cvt_pk_bf16_f32 v214, v64, v65
	v_max_f32_e32 v66, 0, v66
	v_max_f32_e32 v67, 0, v67
	v_mul_f32_e32 v66, v66, v66
	v_mul_f32_e32 v67, v67, v67
	v_cvt_pk_bf16_f32 v215, v66, v67
	v_max_f32_e32 v68, 0, v68
	v_max_f32_e32 v69, 0, v69
	v_mul_f32_e32 v68, v68, v68
	v_mul_f32_e32 v69, v69, v69
	v_cvt_pk_bf16_f32 v216, v68, v69
	v_max_f32_e32 v70, 0, v70
	v_max_f32_e32 v71, 0, v71
	v_mul_f32_e32 v70, v70, v70
	v_mul_f32_e32 v71, v71, v71
	v_cvt_pk_bf16_f32 v217, v70, v71
	v_max_f32_e32 v72, 0, v72
	v_max_f32_e32 v73, 0, v73
	v_mul_f32_e32 v72, v72, v72
	v_mul_f32_e32 v73, v73, v73
	v_cvt_pk_bf16_f32 v218, v72, v73
	v_max_f32_e32 v74, 0, v74
	v_max_f32_e32 v75, 0, v75
	v_mul_f32_e32 v74, v74, v74
	v_mul_f32_e32 v75, v75, v75
	v_cvt_pk_bf16_f32 v219, v74, v75
	v_max_f32_e32 v76, 0, v76
	v_max_f32_e32 v77, 0, v77
	v_mul_f32_e32 v76, v76, v76
	v_mul_f32_e32 v77, v77, v77
	v_cvt_pk_bf16_f32 v220, v76, v77
	v_max_f32_e32 v78, 0, v78
	v_max_f32_e32 v79, 0, v79
	v_mul_f32_e32 v78, v78, v78
	v_mul_f32_e32 v79, v79, v79
	v_cvt_pk_bf16_f32 v221, v78, v79
	v_max_f32_e32 v48, 0, v48
	v_max_f32_e32 v49, 0, v49
	v_mul_f32_e32 v48, v48, v48
	v_mul_f32_e32 v49, v49, v49
	v_cvt_pk_bf16_f32 v222, v48, v49
	v_max_f32_e32 v50, 0, v50
	v_max_f32_e32 v51, 0, v51
	v_mul_f32_e32 v50, v50, v50
	v_mul_f32_e32 v51, v51, v51
	v_cvt_pk_bf16_f32 v223, v50, v51
	v_max_f32_e32 v52, 0, v52
	v_max_f32_e32 v53, 0, v53
	v_mul_f32_e32 v52, v52, v52
	v_mul_f32_e32 v53, v53, v53
	v_cvt_pk_bf16_f32 v224, v52, v53
	v_max_f32_e32 v54, 0, v54
	v_max_f32_e32 v55, 0, v55
	v_mul_f32_e32 v54, v54, v54
	v_mul_f32_e32 v55, v55, v55
	v_cvt_pk_bf16_f32 v225, v54, v55
	v_max_f32_e32 v56, 0, v56
	v_max_f32_e32 v57, 0, v57
	v_mul_f32_e32 v56, v56, v56
	v_mul_f32_e32 v57, v57, v57
	v_cvt_pk_bf16_f32 v226, v56, v57
	v_max_f32_e32 v58, 0, v58
	v_max_f32_e32 v59, 0, v59
	v_mul_f32_e32 v58, v58, v58
	v_mul_f32_e32 v59, v59, v59
	v_cvt_pk_bf16_f32 v227, v58, v59
	v_max_f32_e32 v60, 0, v60
	v_max_f32_e32 v61, 0, v61
	v_mul_f32_e32 v60, v60, v60
	v_mul_f32_e32 v61, v61, v61
	v_cvt_pk_bf16_f32 v228, v60, v61
	v_max_f32_e32 v62, 0, v62
	v_max_f32_e32 v63, 0, v63
	v_mul_f32_e32 v62, v62, v62
	v_mul_f32_e32 v63, v63, v63
	v_cvt_pk_bf16_f32 v229, v62, v63
	v_max_f32_e32 v32, 0, v32
	v_max_f32_e32 v33, 0, v33
	v_mul_f32_e32 v32, v32, v32
	v_mul_f32_e32 v33, v33, v33
	v_cvt_pk_bf16_f32 v230, v32, v33
	v_max_f32_e32 v34, 0, v34
	v_max_f32_e32 v35, 0, v35
	v_mul_f32_e32 v34, v34, v34
	v_mul_f32_e32 v35, v35, v35
	v_cvt_pk_bf16_f32 v231, v34, v35
	v_max_f32_e32 v36, 0, v36
	v_max_f32_e32 v37, 0, v37
	v_mul_f32_e32 v36, v36, v36
	v_mul_f32_e32 v37, v37, v37
	v_cvt_pk_bf16_f32 v232, v36, v37
	v_max_f32_e32 v38, 0, v38
	v_max_f32_e32 v39, 0, v39
	v_mul_f32_e32 v38, v38, v38
	v_mul_f32_e32 v39, v39, v39
	v_cvt_pk_bf16_f32 v233, v38, v39
	v_max_f32_e32 v40, 0, v40
	v_max_f32_e32 v41, 0, v41
	v_mul_f32_e32 v40, v40, v40
	v_mul_f32_e32 v41, v41, v41
	v_cvt_pk_bf16_f32 v234, v40, v41
	v_max_f32_e32 v42, 0, v42
	v_max_f32_e32 v43, 0, v43
	v_mul_f32_e32 v42, v42, v42
	v_mul_f32_e32 v43, v43, v43
	v_cvt_pk_bf16_f32 v235, v42, v43
	v_max_f32_e32 v44, 0, v44
	v_max_f32_e32 v45, 0, v45
	v_mul_f32_e32 v44, v44, v44
	v_mul_f32_e32 v45, v45, v45
	v_cvt_pk_bf16_f32 v236, v44, v45
	v_max_f32_e32 v46, 0, v46
	v_max_f32_e32 v47, 0, v47
	v_mul_f32_e32 v46, v46, v46
	v_mul_f32_e32 v47, v47, v47
	v_cvt_pk_bf16_f32 v237, v46, v47
	v_max_f32_e32 v16, 0, v16
	v_max_f32_e32 v17, 0, v17
	v_mul_f32_e32 v16, v16, v16
	v_mul_f32_e32 v17, v17, v17
	v_cvt_pk_bf16_f32 v238, v16, v17
	v_max_f32_e32 v18, 0, v18
	v_max_f32_e32 v19, 0, v19
	v_mul_f32_e32 v18, v18, v18
	v_mul_f32_e32 v19, v19, v19
	v_cvt_pk_bf16_f32 v239, v18, v19
	v_max_f32_e32 v20, 0, v20
	v_max_f32_e32 v21, 0, v21
	v_mul_f32_e32 v20, v20, v20
	v_mul_f32_e32 v21, v21, v21
	v_cvt_pk_bf16_f32 v240, v20, v21
	v_max_f32_e32 v22, 0, v22
	v_max_f32_e32 v23, 0, v23
	v_mul_f32_e32 v22, v22, v22
	v_mul_f32_e32 v23, v23, v23
	v_cvt_pk_bf16_f32 v241, v22, v23
	v_max_f32_e32 v24, 0, v24
	v_max_f32_e32 v25, 0, v25
	v_mul_f32_e32 v24, v24, v24
	v_mul_f32_e32 v25, v25, v25
	v_cvt_pk_bf16_f32 v242, v24, v25
	v_max_f32_e32 v26, 0, v26
	v_max_f32_e32 v27, 0, v27
	v_mul_f32_e32 v26, v26, v26
	v_mul_f32_e32 v27, v27, v27
	v_cvt_pk_bf16_f32 v243, v26, v27
	v_max_f32_e32 v28, 0, v28
	v_max_f32_e32 v29, 0, v29
	v_mul_f32_e32 v28, v28, v28
	v_mul_f32_e32 v29, v29, v29
	v_cvt_pk_bf16_f32 v244, v28, v29
	v_max_f32_e32 v30, 0, v30
	v_max_f32_e32 v31, 0, v31
	v_mul_f32_e32 v30, v30, v30
	v_mul_f32_e32 v31, v31, v31
	v_cvt_pk_bf16_f32 v245, v30, v31
	v_max_f32_e32 v0, 0, v0
	v_max_f32_e32 v1, 0, v1
	v_mul_f32_e32 v0, v0, v0
	v_mul_f32_e32 v1, v1, v1
	v_cvt_pk_bf16_f32 v246, v0, v1
	v_max_f32_e32 v2, 0, v2
	v_max_f32_e32 v3, 0, v3
	v_mul_f32_e32 v2, v2, v2
	v_mul_f32_e32 v3, v3, v3
	v_cvt_pk_bf16_f32 v247, v2, v3
	v_max_f32_e32 v4, 0, v4
	v_max_f32_e32 v5, 0, v5
	v_mul_f32_e32 v4, v4, v4
	v_mul_f32_e32 v5, v5, v5
	v_cvt_pk_bf16_f32 v248, v4, v5
	v_max_f32_e32 v6, 0, v6
	v_max_f32_e32 v7, 0, v7
	v_mul_f32_e32 v6, v6, v6
	v_mul_f32_e32 v7, v7, v7
	v_cvt_pk_bf16_f32 v249, v6, v7
	v_max_f32_e32 v8, 0, v8
	v_max_f32_e32 v9, 0, v9
	v_mul_f32_e32 v8, v8, v8
	v_mul_f32_e32 v9, v9, v9
	v_cvt_pk_bf16_f32 v250, v8, v9
	v_max_f32_e32 v10, 0, v10
	v_max_f32_e32 v11, 0, v11
	v_mul_f32_e32 v10, v10, v10
	v_mul_f32_e32 v11, v11, v11
	v_cvt_pk_bf16_f32 v251, v10, v11
	v_max_f32_e32 v12, 0, v12
	v_max_f32_e32 v13, 0, v13
	v_mul_f32_e32 v12, v12, v12
	v_mul_f32_e32 v13, v13, v13
	v_cvt_pk_bf16_f32 v252, v12, v13
	v_max_f32_e32 v14, 0, v14
	v_max_f32_e32 v15, 0, v15
	v_mul_f32_e32 v14, v14, v14
	v_mul_f32_e32 v15, v15, v15
	v_cvt_pk_bf16_f32 v253, v14, v15
	s_add_i32 s57, s57, s21
	s_add_i32 s56, s56, s21
	s_cmpk_lt_u32 s57, 0x200
	s_cbranch_scc1 .LBB0_1976
	v_and_b32_e32 v3, 15, v182
	v_lshrrev_b32_e32 v4, 4, v182
	v_mul_u32_u24_e32 v2, 0x2000, v4
	v_lshl_add_u32 v2, v3, 4, v2
	v_mul_u32_u24_e32 v1, 0x110, v4
	v_lshl_add_u32 v1, v3, 4, v1
	v_lshrrev_b32_e32 v3, 7, v182
	v_bfe_u32 v4, v182, 5, 1
	v_lshlrev_b32_e32 v3, 6, v3
	v_lshl_or_b32 v3, v4, 2, v3
	v_mul_u32_u24_e32 v3, 136, v3
	v_and_b32_e32 v4, 0x5f, v182
	v_add_lshl_u32 v0, v3, v4, 1
	s_barrier
	ds_write_b16 v0, v190
	ds_write_b16_d16_hi v0, v190 offset:272
	ds_write_b16 v0, v191 offset:544
	ds_write_b16_d16_hi v0, v191 offset:816
	ds_write_b16 v0, v192 offset:2176
	ds_write_b16_d16_hi v0, v192 offset:2448
	ds_write_b16 v0, v193 offset:2720
	ds_write_b16_d16_hi v0, v193 offset:2992
	ds_write_b16 v0, v194 offset:4352
	ds_write_b16_d16_hi v0, v194 offset:4624
	ds_write_b16 v0, v195 offset:4896
	ds_write_b16_d16_hi v0, v195 offset:5168
	ds_write_b16 v0, v196 offset:6528
	ds_write_b16_d16_hi v0, v196 offset:6800
	ds_write_b16 v0, v197 offset:7072
	ds_write_b16_d16_hi v0, v197 offset:7344
	ds_write_b16 v0, v198 offset:64
	ds_write_b16_d16_hi v0, v198 offset:336
	ds_write_b16 v0, v199 offset:608
	ds_write_b16_d16_hi v0, v199 offset:880
	ds_write_b16 v0, v200 offset:2240
	ds_write_b16_d16_hi v0, v200 offset:2512
	ds_write_b16 v0, v201 offset:2784
	ds_write_b16_d16_hi v0, v201 offset:3056
	ds_write_b16 v0, v202 offset:4416
	ds_write_b16_d16_hi v0, v202 offset:4688
	ds_write_b16 v0, v203 offset:4960
	ds_write_b16_d16_hi v0, v203 offset:5232
	ds_write_b16 v0, v204 offset:6592
	ds_write_b16_d16_hi v0, v204 offset:6864
	ds_write_b16 v0, v205 offset:7136
	ds_write_b16_d16_hi v0, v205 offset:7408
	ds_write_b16 v0, v206 offset:8704
	ds_write_b16_d16_hi v0, v206 offset:8976
	ds_write_b16 v0, v207 offset:9248
	ds_write_b16_d16_hi v0, v207 offset:9520
	ds_write_b16 v0, v208 offset:10880
	ds_write_b16_d16_hi v0, v208 offset:11152
	ds_write_b16 v0, v209 offset:11424
	ds_write_b16_d16_hi v0, v209 offset:11696
	ds_write_b16 v0, v210 offset:13056
	ds_write_b16_d16_hi v0, v210 offset:13328
	ds_write_b16 v0, v211 offset:13600
	ds_write_b16_d16_hi v0, v211 offset:13872
	ds_write_b16 v0, v212 offset:15232
	ds_write_b16_d16_hi v0, v212 offset:15504
	ds_write_b16 v0, v213 offset:15776
	ds_write_b16_d16_hi v0, v213 offset:16048
	ds_write_b16 v0, v214 offset:8768
	ds_write_b16_d16_hi v0, v214 offset:9040
	ds_write_b16 v0, v215 offset:9312
	ds_write_b16_d16_hi v0, v215 offset:9584
	ds_write_b16 v0, v216 offset:10944
	ds_write_b16_d16_hi v0, v216 offset:11216
	ds_write_b16 v0, v217 offset:11488
	ds_write_b16_d16_hi v0, v217 offset:11760
	ds_write_b16 v0, v218 offset:13120
	ds_write_b16_d16_hi v0, v218 offset:13392
	ds_write_b16 v0, v219 offset:13664
	ds_write_b16_d16_hi v0, v219 offset:13936
	ds_write_b16 v0, v220 offset:15296
	ds_write_b16_d16_hi v0, v220 offset:15568
	ds_write_b16 v0, v221 offset:15840
	ds_write_b16_d16_hi v0, v221 offset:16112
	s_waitcnt lgkmcnt(0)
	s_barrier
	ds_read_b128 v[8:11], v1
	ds_read_b128 v[12:15], v1 offset:4352
	ds_read_b128 v[16:19], v1 offset:8704
	ds_read_b128 v[20:23], v1 offset:13056
	ds_read_b128 v[24:27], v1 offset:17408
	ds_read_b128 v[28:31], v1 offset:21760
	ds_read_b128 v[32:35], v1 offset:26112
	ds_read_b128 v[36:39], v1 offset:30464
	s_add_u32 s38, s44, 0x0
	s_addc_u32 s39, s45, 0
	s_waitcnt lgkmcnt(7)
	global_store_dwordx4 v2, v[8:11], s[38:39]
	s_add_u32 s38, s44, 0x20000
	s_addc_u32 s39, s45, 0
	s_waitcnt lgkmcnt(6)
	global_store_dwordx4 v2, v[12:15], s[38:39]
	s_add_u32 s38, s44, 0x40000
	s_addc_u32 s39, s45, 0
	s_waitcnt lgkmcnt(5)
	global_store_dwordx4 v2, v[16:19], s[38:39]
	s_add_u32 s38, s44, 0x60000
	s_addc_u32 s39, s45, 0
	s_waitcnt lgkmcnt(4)
	global_store_dwordx4 v2, v[20:23], s[38:39]
	s_add_u32 s38, s44, 0x100000
	s_addc_u32 s39, s45, 0
	s_waitcnt lgkmcnt(3)
	global_store_dwordx4 v2, v[24:27], s[38:39]
	s_add_u32 s38, s44, 0x120000
	s_addc_u32 s39, s45, 0
	s_waitcnt lgkmcnt(2)
	global_store_dwordx4 v2, v[28:31], s[38:39]
	s_add_u32 s38, s44, 0x140000
	s_addc_u32 s39, s45, 0
	s_waitcnt lgkmcnt(1)
	global_store_dwordx4 v2, v[32:35], s[38:39]
	s_add_u32 s38, s44, 0x160000
	s_addc_u32 s39, s45, 0
	s_waitcnt lgkmcnt(0)
	global_store_dwordx4 v2, v[36:39], s[38:39]
	s_barrier
	ds_write_b16 v0, v222
	ds_write_b16_d16_hi v0, v222 offset:272
	ds_write_b16 v0, v223 offset:544
	ds_write_b16_d16_hi v0, v223 offset:816
	ds_write_b16 v0, v224 offset:2176
	ds_write_b16_d16_hi v0, v224 offset:2448
	ds_write_b16 v0, v225 offset:2720
	ds_write_b16_d16_hi v0, v225 offset:2992
	ds_write_b16 v0, v226 offset:4352
	ds_write_b16_d16_hi v0, v226 offset:4624
	ds_write_b16 v0, v227 offset:4896
	ds_write_b16_d16_hi v0, v227 offset:5168
	ds_write_b16 v0, v228 offset:6528
	ds_write_b16_d16_hi v0, v228 offset:6800
	ds_write_b16 v0, v229 offset:7072
	ds_write_b16_d16_hi v0, v229 offset:7344
	ds_write_b16 v0, v230 offset:64
	ds_write_b16_d16_hi v0, v230 offset:336
	ds_write_b16 v0, v231 offset:608
	ds_write_b16_d16_hi v0, v231 offset:880
	ds_write_b16 v0, v232 offset:2240
	ds_write_b16_d16_hi v0, v232 offset:2512
	ds_write_b16 v0, v233 offset:2784
	ds_write_b16_d16_hi v0, v233 offset:3056
	ds_write_b16 v0, v234 offset:4416
	ds_write_b16_d16_hi v0, v234 offset:4688
	ds_write_b16 v0, v235 offset:4960
	ds_write_b16_d16_hi v0, v235 offset:5232
	ds_write_b16 v0, v236 offset:6592
	ds_write_b16_d16_hi v0, v236 offset:6864
	ds_write_b16 v0, v237 offset:7136
	ds_write_b16_d16_hi v0, v237 offset:7408
	ds_write_b16 v0, v238 offset:8704
	ds_write_b16_d16_hi v0, v238 offset:8976
	ds_write_b16 v0, v239 offset:9248
	ds_write_b16_d16_hi v0, v239 offset:9520
	ds_write_b16 v0, v240 offset:10880
	ds_write_b16_d16_hi v0, v240 offset:11152
	ds_write_b16 v0, v241 offset:11424
	ds_write_b16_d16_hi v0, v241 offset:11696
	ds_write_b16 v0, v242 offset:13056
	ds_write_b16_d16_hi v0, v242 offset:13328
	ds_write_b16 v0, v243 offset:13600
	ds_write_b16_d16_hi v0, v243 offset:13872
	ds_write_b16 v0, v244 offset:15232
	ds_write_b16_d16_hi v0, v244 offset:15504
	ds_write_b16 v0, v245 offset:15776
	ds_write_b16_d16_hi v0, v245 offset:16048
	ds_write_b16 v0, v246 offset:8768
	ds_write_b16_d16_hi v0, v246 offset:9040
	ds_write_b16 v0, v247 offset:9312
	ds_write_b16_d16_hi v0, v247 offset:9584
	ds_write_b16 v0, v248 offset:10944
	ds_write_b16_d16_hi v0, v248 offset:11216
	ds_write_b16 v0, v249 offset:11488
	ds_write_b16_d16_hi v0, v249 offset:11760
	ds_write_b16 v0, v250 offset:13120
	ds_write_b16_d16_hi v0, v250 offset:13392
	ds_write_b16 v0, v251 offset:13664
	ds_write_b16_d16_hi v0, v251 offset:13936
	ds_write_b16 v0, v252 offset:15296
	ds_write_b16_d16_hi v0, v252 offset:15568
	ds_write_b16 v0, v253 offset:15840
	ds_write_b16_d16_hi v0, v253 offset:16112
	s_waitcnt lgkmcnt(0)
	s_barrier
	ds_read_b128 v[8:11], v1
	ds_read_b128 v[12:15], v1 offset:4352
	ds_read_b128 v[16:19], v1 offset:8704
	ds_read_b128 v[20:23], v1 offset:13056
	ds_read_b128 v[24:27], v1 offset:17408
	ds_read_b128 v[28:31], v1 offset:21760
	ds_read_b128 v[32:35], v1 offset:26112
	ds_read_b128 v[36:39], v1 offset:30464
	s_add_u32 s38, s44, 0x80000
	s_addc_u32 s39, s45, 0
	s_waitcnt lgkmcnt(7)
	global_store_dwordx4 v2, v[8:11], s[38:39]
	s_add_u32 s38, s44, 0xa0000
	s_addc_u32 s39, s45, 0
	s_waitcnt lgkmcnt(6)
	global_store_dwordx4 v2, v[12:15], s[38:39]
	s_add_u32 s38, s44, 0xc0000
	s_addc_u32 s39, s45, 0
	s_waitcnt lgkmcnt(5)
	global_store_dwordx4 v2, v[16:19], s[38:39]
	s_add_u32 s38, s44, 0xe0000
	s_addc_u32 s39, s45, 0
	s_waitcnt lgkmcnt(4)
	global_store_dwordx4 v2, v[20:23], s[38:39]
	s_add_u32 s38, s44, 0x180000
	s_addc_u32 s39, s45, 0
	s_waitcnt lgkmcnt(3)
	global_store_dwordx4 v2, v[24:27], s[38:39]
	s_add_u32 s38, s44, 0x1a0000
	s_addc_u32 s39, s45, 0
	s_waitcnt lgkmcnt(2)
	global_store_dwordx4 v2, v[28:31], s[38:39]
	s_add_u32 s38, s44, 0x1c0000
	s_addc_u32 s39, s45, 0
	s_waitcnt lgkmcnt(1)
	global_store_dwordx4 v2, v[32:35], s[38:39]
	s_add_u32 s38, s44, 0x1e0000
	s_addc_u32 s39, s45, 0
	s_waitcnt lgkmcnt(0)
	global_store_dwordx4 v2, v[36:39], s[38:39]
	s_mov_b32 s43, 0
	s_branch .LBB0_1969
